# write-through GEMM epilogue stores; de-serialized loads in s5 bu stage, prep_conv tile load, sgu item (all loads issued up front)
# speedup vs baseline: 1.1617x; 1.0269x over previous
.Lgm_f1_cnt:
	s_add_u32 s30, s30, 16
	s_add_u32 s4, s4, s52
	s_cmp_lt_u32 s4, s54
	s_cbranch_scc1 .Lgm_f1_cnt
	s_add_u32 s48, s96, 0x2e24000
	s_addc_u32 s49, s97, 0
	s_mul_i32 s4, s36, 0x800000
	s_add_u32 s50, s96, 0xd80000
	s_addc_u32 s51, s97, 0
	s_add_u32 s50, s50, s4
	s_addc_u32 s51, s51, 0
	v_and_b32_e32 v0, 63, v206
	v_lshrrev_b32_e32 v1, 6, v206
	v_lshrrev_b32_e32 v3, 3, v0
	v_and_b32_e32 v4, 7, v0
	v_readfirstlane_b32 s42, v1
	v_xor_b32_e32 v4, v4, v3
	v_lshl_add_u32 v3, v1, 3, v3
	v_lshlrev_b32_e32 v3, 11, v3
	v_lshl_add_u32 v148, v4, 4, v3
	v_add_u32_e32 v149, 0x20000, v148
	v_add_u32_e32 v150, 0x40000, v148
	v_and_b32_e32 v5, 15, v0
	v_lshrrev_b32_e32 v6, 4, v0
	v_and_b32_e32 v7, 7, v5
	v_xor_b32_e32 v7, v7, v6
	v_lshlrev_b32_e32 v7, 4, v7
	v_lshrrev_b32_e32 v8, 1, v1
	v_and_b32_e32 v9, 1, v1
	v_mul_u32_u24_e32 v10, 48, v8
	v_add_u32_e32 v11, v10, v5
	v_lshl_add_u32 v151, v11, 7, v7
	v_xor_b32_e32 v152, 64, v151
	v_lshl_add_u32 v11, v9, 6, v5
	v_lshl_add_u32 v153, v11, 7, v7
	v_add_u32_e32 v153, 0x6000, v153
	v_xor_b32_e32 v154, 64, v153
	s_mul_i32 s5, s42, 4352
	s_mov_b32 s6, 0x1ec10
	s_cmp_lt_u32 s42, 4
	s_cselect_b32 s6, 0x1e000, s6
	s_add_u32 s5, s5, s6
	s_mov_b32 s43, s5
	v_mul_u32_u24_e32 v11, 1088, v6
	v_lshl_add_u32 v11, v5, 2, v11
	v_add_u32_e32 v155, s5, v11
	v_mul_u32_u24_e32 v11, 272, v6
	v_lshl_add_u32 v11, v5, 4, v11
	v_add_u32_e32 v156, s5, v11
	v_add_u32_e32 v11, v10, v6
	v_lshlrev_b32_e32 v12, 6, v9
	v_lshl_add_u32 v12, v5, 2, v12
	s_mov_b32 s4, 0x2000
	v_mul_lo_u32 v13, v11, s4
	v_lshl_add_u32 v157, v12, 1, v13
	s_lshl_b32 s42, s42, 10
	v_mov_b32_e32 v44, 0
	v_mov_b32_e32 v45, 0
	v_mov_b32_e32 v46, 0
	v_mov_b32_e32 v47, 0
	v_mov_b32_e32 v48, 0
	v_mov_b32_e32 v49, 0
	v_mov_b32_e32 v50, 0
	v_mov_b32_e32 v51, 0
	v_mov_b32_e32 v52, 0
	v_mov_b32_e32 v53, 0
	v_mov_b32_e32 v54, 0
	v_mov_b32_e32 v55, 0
	v_mov_b32_e32 v56, 0
	v_mov_b32_e32 v57, 0
	v_mov_b32_e32 v58, 0
	v_mov_b32_e32 v59, 0
	v_mov_b32_e32 v60, 0
	v_mov_b32_e32 v61, 0
	v_mov_b32_e32 v62, 0
	v_mov_b32_e32 v63, 0
	v_mov_b32_e32 v64, 0
	v_mov_b32_e32 v65, 0
	v_mov_b32_e32 v66, 0
	v_mov_b32_e32 v67, 0
	v_mov_b32_e32 v68, 0
	v_mov_b32_e32 v69, 0
	v_mov_b32_e32 v70, 0
	v_mov_b32_e32 v71, 0
	v_mov_b32_e32 v72, 0
	v_mov_b32_e32 v73, 0
	v_mov_b32_e32 v74, 0
	v_mov_b32_e32 v75, 0
	v_mov_b32_e32 v76, 0
	v_mov_b32_e32 v77, 0
	v_mov_b32_e32 v78, 0
	v_mov_b32_e32 v79, 0
	v_mov_b32_e32 v80, 0
	v_mov_b32_e32 v81, 0
	v_mov_b32_e32 v82, 0
	v_mov_b32_e32 v83, 0
	v_mov_b32_e32 v84, 0
	v_mov_b32_e32 v85, 0
	v_mov_b32_e32 v86, 0
	v_mov_b32_e32 v87, 0
	v_mov_b32_e32 v88, 0
	v_mov_b32_e32 v89, 0
	v_mov_b32_e32 v90, 0
	v_mov_b32_e32 v91, 0
	s_mov_b32 s31, 0
	s_mov_b32 s34, 0
	s_mov_b32 s35, s53
	s_mov_b32 s38, s53
	s_mov_b32 s39, 0
	s_mov_b32 s40, 0
	s_mov_b32 s41, s42
	s_and_b32 s4, s38, 31
	s_mul_i32 s4, s4, 0x60000
	s_add_u32 s44, s48, s4
	s_addc_u32 s45, s49, 0
	s_lshr_b32 s4, s38, 5
	s_mul_i32 s4, s4, 0x40000
	s_add_u32 s46, s50, s4
	s_addc_u32 s47, s51, 0
	s_add_u32 m0, s41, 0x0
	s_nop 0
	global_load_lds_dwordx4 v148, s[44:45]
	s_add_u32 m0, s41, 0x2000
	s_nop 0
	global_load_lds_dwordx4 v149, s[44:45]
	s_add_u32 m0, s41, 0x4000
	s_nop 0
	global_load_lds_dwordx4 v150, s[44:45]
	s_add_u32 m0, s41, 0x6000
	s_nop 0
	global_load_lds_dwordx4 v148, s[46:47]
	s_add_u32 m0, s41, 0x8000
	s_nop 0
	global_load_lds_dwordx4 v149, s[46:47]
	s_add_u32 s39, s39, 1
	s_add_u32 s44, s44, 0x80
	s_addc_u32 s45, s45, 0
	s_add_u32 s46, s46, 0x80
	s_addc_u32 s47, s47, 0
	s_cmp_lt_u32 s39, 16
	s_cbranch_scc1 .Lgm_f1_dadv1
	s_mov_b32 s39, 0
	s_add_u32 s4, s38, s52
	s_cmp_lt_u32 s4, s54
	s_cselect_b32 s38, s4, s38
	s_and_b32 s4, s38, 31
	s_mul_i32 s4, s4, 0x60000
	s_add_u32 s44, s48, s4
	s_addc_u32 s45, s49, 0
	s_lshr_b32 s4, s38, 5
	s_mul_i32 s4, s4, 0x40000
	s_add_u32 s46, s50, s4
	s_addc_u32 s47, s51, 0

.Lgm_f1_dadv3:
	ds_read_b128 v[120:123], v152 offset:0
	ds_read_b128 v[124:127], v152 offset:2048
	ds_read_b128 v[128:131], v152 offset:4096
	ds_read_b128 v[132:135], v154 offset:0
	ds_read_b128 v[136:139], v154 offset:2048
	ds_read_b128 v[140:143], v154 offset:4096
	ds_read_b128 v[144:147], v154 offset:6144
	s_waitcnt lgkmcnt(10)
	v_mfma_f32_16x16x32_bf16 v[44:47], v[92:95], v[104:107], v[44:47]
	v_mfma_f32_16x16x32_bf16 v[60:63], v[96:99], v[104:107], v[60:63]
	v_mfma_f32_16x16x32_bf16 v[76:79], v[100:103], v[104:107], v[76:79]
	s_waitcnt lgkmcnt(9)
	v_mfma_f32_16x16x32_bf16 v[48:51], v[92:95], v[108:111], v[48:51]
	v_mfma_f32_16x16x32_bf16 v[64:67], v[96:99], v[108:111], v[64:67]
	v_mfma_f32_16x16x32_bf16 v[80:83], v[100:103], v[108:111], v[80:83]
	s_waitcnt lgkmcnt(8)
	v_mfma_f32_16x16x32_bf16 v[52:55], v[92:95], v[112:115], v[52:55]
	v_mfma_f32_16x16x32_bf16 v[68:71], v[96:99], v[112:115], v[68:71]
	v_mfma_f32_16x16x32_bf16 v[84:87], v[100:103], v[112:115], v[84:87]
	s_waitcnt lgkmcnt(7)
	v_mfma_f32_16x16x32_bf16 v[56:59], v[92:95], v[116:119], v[56:59]
	v_mfma_f32_16x16x32_bf16 v[72:75], v[96:99], v[116:119], v[72:75]
	v_mfma_f32_16x16x32_bf16 v[88:91], v[100:103], v[116:119], v[88:91]
	s_waitcnt lgkmcnt(0)
	s_add_u32 s34, s34, 1
	s_cmp_lt_u32 s34, 16
	s_cbranch_scc1 .Lgm_f1_next_a
	v_mfma_f32_16x16x32_bf16 v[44:47], v[120:123], v[132:135], v[44:47]
	v_mfma_f32_16x16x32_bf16 v[60:63], v[124:127], v[132:135], v[60:63]
	v_mfma_f32_16x16x32_bf16 v[76:79], v[128:131], v[132:135], v[76:79]
	v_mfma_f32_16x16x32_bf16 v[48:51], v[120:123], v[136:139], v[48:51]
	v_mfma_f32_16x16x32_bf16 v[64:67], v[124:127], v[136:139], v[64:67]
	v_mfma_f32_16x16x32_bf16 v[80:83], v[128:131], v[136:139], v[80:83]
	v_mfma_f32_16x16x32_bf16 v[52:55], v[120:123], v[140:143], v[52:55]
	v_mfma_f32_16x16x32_bf16 v[68:71], v[124:127], v[140:143], v[68:71]
	v_mfma_f32_16x16x32_bf16 v[84:87], v[128:131], v[140:143], v[84:87]
	v_mfma_f32_16x16x32_bf16 v[56:59], v[120:123], v[144:147], v[56:59]
	v_mfma_f32_16x16x32_bf16 v[72:75], v[124:127], v[144:147], v[72:75]
	v_mfma_f32_16x16x32_bf16 v[88:91], v[128:131], v[144:147], v[88:91]
	s_and_b32 s6, s35, 31
	s_mul_i32 s6, s6, 192
	s_lshr_b32 s7, s35, 5
	s_lshl_b32 s7, s7, 7
	s_nop 7
	s_mul_i32 s4, s6, 0x2000
	s_lshl_b32 s5, s7, 1
	s_add_u32 s4, s4, s5
	v_add_u32_e32 v158, s4, v157
	ds_write_b32 v155, v44 offset:0
	ds_write_b32 v155, v45 offset:272
	ds_write_b32 v155, v46 offset:544
	ds_write_b32 v155, v47 offset:816
	ds_write_b32 v155, v48 offset:64
	ds_write_b32 v155, v49 offset:336
	ds_write_b32 v155, v50 offset:608
	ds_write_b32 v155, v51 offset:880
	ds_write_b32 v155, v52 offset:128
	ds_write_b32 v155, v53 offset:400
	ds_write_b32 v155, v54 offset:672
	ds_write_b32 v155, v55 offset:944
	ds_write_b32 v155, v56 offset:192
	ds_write_b32 v155, v57 offset:464
	ds_write_b32 v155, v58 offset:736
	ds_write_b32 v155, v59 offset:1008
	s_waitcnt lgkmcnt(0)
	ds_read_b128 v[16:19], v156 offset:0
	ds_read_b128 v[20:23], v156 offset:1088
	ds_read_b128 v[24:27], v156 offset:2176
	ds_read_b128 v[28:31], v156 offset:3264
	s_waitcnt lgkmcnt(3)
	v_max_f32_e32 v16, 0, v16
	v_max_f32_e32 v17, 0, v17
	v_max_f32_e32 v18, 0, v18
	v_max_f32_e32 v19, 0, v19
	v_mul_f32_e32 v16, v16, v16
	v_mul_f32_e32 v17, v17, v17
	v_mul_f32_e32 v18, v18, v18
	v_mul_f32_e32 v19, v19, v19
	v_cvt_pk_bf16_f32 v32, v16, v17
	v_cvt_pk_bf16_f32 v33, v18, v19
	global_store_dwordx2 v158, v[32:33], s[56:57] sc0 sc1
	v_add_u32_e32 v158, 0x8000, v158
	s_waitcnt lgkmcnt(2)
	v_max_f32_e32 v20, 0, v20
	v_max_f32_e32 v21, 0, v21
	v_max_f32_e32 v22, 0, v22
	v_max_f32_e32 v23, 0, v23
	v_mul_f32_e32 v20, v20, v20
	v_mul_f32_e32 v21, v21, v21
	v_mul_f32_e32 v22, v22, v22
	v_mul_f32_e32 v23, v23, v23
	v_cvt_pk_bf16_f32 v34, v20, v21
	v_cvt_pk_bf16_f32 v35, v22, v23
	global_store_dwordx2 v158, v[34:35], s[56:57] sc0 sc1
	v_add_u32_e32 v158, 0x8000, v158
	s_waitcnt lgkmcnt(1)
	v_max_f32_e32 v24, 0, v24
	v_max_f32_e32 v25, 0, v25
	v_max_f32_e32 v26, 0, v26
	v_max_f32_e32 v27, 0, v27
	v_mul_f32_e32 v24, v24, v24
	v_mul_f32_e32 v25, v25, v25
	v_mul_f32_e32 v26, v26, v26
	v_mul_f32_e32 v27, v27, v27
	v_cvt_pk_bf16_f32 v36, v24, v25
	v_cvt_pk_bf16_f32 v37, v26, v27
	global_store_dwordx2 v158, v[36:37], s[56:57] sc0 sc1
	v_add_u32_e32 v158, 0x8000, v158
	s_waitcnt lgkmcnt(0)
	v_max_f32_e32 v28, 0, v28
	v_max_f32_e32 v29, 0, v29
	v_max_f32_e32 v30, 0, v30
	v_max_f32_e32 v31, 0, v31
	v_mul_f32_e32 v28, v28, v28
	v_mul_f32_e32 v29, v29, v29
	v_mul_f32_e32 v30, v30, v30
	v_mul_f32_e32 v31, v31, v31
	v_cvt_pk_bf16_f32 v38, v28, v29
	v_cvt_pk_bf16_f32 v39, v30, v31
	global_store_dwordx2 v158, v[38:39], s[56:57] sc0 sc1
	v_add_u32_e32 v158, 0x8000, v158
	ds_write_b32 v155, v60 offset:0
	ds_write_b32 v155, v61 offset:272
	ds_write_b32 v155, v62 offset:544
	ds_write_b32 v155, v63 offset:816
	ds_write_b32 v155, v64 offset:64
	ds_write_b32 v155, v65 offset:336
	ds_write_b32 v155, v66 offset:608
	ds_write_b32 v155, v67 offset:880
	ds_write_b32 v155, v68 offset:128
	ds_write_b32 v155, v69 offset:400
	ds_write_b32 v155, v70 offset:672
	ds_write_b32 v155, v71 offset:944
	ds_write_b32 v155, v72 offset:192
	ds_write_b32 v155, v73 offset:464
	ds_write_b32 v155, v74 offset:736
	ds_write_b32 v155, v75 offset:1008
	s_waitcnt lgkmcnt(0)
	ds_read_b128 v[16:19], v156 offset:0
	ds_read_b128 v[20:23], v156 offset:1088
	ds_read_b128 v[24:27], v156 offset:2176
	ds_read_b128 v[28:31], v156 offset:3264
	s_waitcnt lgkmcnt(3)
	v_max_f32_e32 v16, 0, v16
	v_max_f32_e32 v17, 0, v17
	v_max_f32_e32 v18, 0, v18
	v_max_f32_e32 v19, 0, v19
	v_mul_f32_e32 v16, v16, v16
	v_mul_f32_e32 v17, v17, v17
	v_mul_f32_e32 v18, v18, v18
	v_mul_f32_e32 v19, v19, v19
	v_cvt_pk_bf16_f32 v32, v16, v17
	v_cvt_pk_bf16_f32 v33, v18, v19
	global_store_dwordx2 v158, v[32:33], s[56:57] sc0 sc1
	v_add_u32_e32 v158, 0x8000, v158
	s_waitcnt lgkmcnt(2)
	v_max_f32_e32 v20, 0, v20
	v_max_f32_e32 v21, 0, v21
	v_max_f32_e32 v22, 0, v22
	v_max_f32_e32 v23, 0, v23
	v_mul_f32_e32 v20, v20, v20
	v_mul_f32_e32 v21, v21, v21
	v_mul_f32_e32 v22, v22, v22
	v_mul_f32_e32 v23, v23, v23
	v_cvt_pk_bf16_f32 v34, v20, v21
	v_cvt_pk_bf16_f32 v35, v22, v23
	global_store_dwordx2 v158, v[34:35], s[56:57] sc0 sc1
	v_add_u32_e32 v158, 0x8000, v158
	s_waitcnt lgkmcnt(1)
	v_max_f32_e32 v24, 0, v24
	v_max_f32_e32 v25, 0, v25
	v_max_f32_e32 v26, 0, v26
	v_max_f32_e32 v27, 0, v27
	v_mul_f32_e32 v24, v24, v24
	v_mul_f32_e32 v25, v25, v25
	v_mul_f32_e32 v26, v26, v26
	v_mul_f32_e32 v27, v27, v27
	v_cvt_pk_bf16_f32 v36, v24, v25
	v_cvt_pk_bf16_f32 v37, v26, v27
	global_store_dwordx2 v158, v[36:37], s[56:57] sc0 sc1
	v_add_u32_e32 v158, 0x8000, v158
	s_waitcnt lgkmcnt(0)
	v_max_f32_e32 v28, 0, v28
	v_max_f32_e32 v29, 0, v29
	v_max_f32_e32 v30, 0, v30
	v_max_f32_e32 v31, 0, v31
	v_mul_f32_e32 v28, v28, v28
	v_mul_f32_e32 v29, v29, v29
	v_mul_f32_e32 v30, v30, v30
	v_mul_f32_e32 v31, v31, v31
	v_cvt_pk_bf16_f32 v38, v28, v29
	v_cvt_pk_bf16_f32 v39, v30, v31
	global_store_dwordx2 v158, v[38:39], s[56:57] sc0 sc1
	v_add_u32_e32 v158, 0x8000, v158
	ds_write_b32 v155, v76 offset:0
	ds_write_b32 v155, v77 offset:272
	ds_write_b32 v155, v78 offset:544
	ds_write_b32 v155, v79 offset:816
	ds_write_b32 v155, v80 offset:64
	ds_write_b32 v155, v81 offset:336
	ds_write_b32 v155, v82 offset:608
	ds_write_b32 v155, v83 offset:880
	ds_write_b32 v155, v84 offset:128
	ds_write_b32 v155, v85 offset:400
	ds_write_b32 v155, v86 offset:672
	ds_write_b32 v155, v87 offset:944
	ds_write_b32 v155, v88 offset:192
	ds_write_b32 v155, v89 offset:464
	ds_write_b32 v155, v90 offset:736
	ds_write_b32 v155, v91 offset:1008
	s_waitcnt lgkmcnt(0)
	ds_read_b128 v[16:19], v156 offset:0
	ds_read_b128 v[20:23], v156 offset:1088
	ds_read_b128 v[24:27], v156 offset:2176
	ds_read_b128 v[28:31], v156 offset:3264
	s_waitcnt lgkmcnt(3)
	v_max_f32_e32 v16, 0, v16
	v_max_f32_e32 v17, 0, v17
	v_max_f32_e32 v18, 0, v18
	v_max_f32_e32 v19, 0, v19
	v_mul_f32_e32 v16, v16, v16
	v_mul_f32_e32 v17, v17, v17
	v_mul_f32_e32 v18, v18, v18
	v_mul_f32_e32 v19, v19, v19
	v_cvt_pk_bf16_f32 v32, v16, v17
	v_cvt_pk_bf16_f32 v33, v18, v19
	global_store_dwordx2 v158, v[32:33], s[56:57] sc0 sc1
	v_add_u32_e32 v158, 0x8000, v158
	s_waitcnt lgkmcnt(2)
	v_max_f32_e32 v20, 0, v20
	v_max_f32_e32 v21, 0, v21
	v_max_f32_e32 v22, 0, v22
	v_max_f32_e32 v23, 0, v23
	v_mul_f32_e32 v20, v20, v20
	v_mul_f32_e32 v21, v21, v21
	v_mul_f32_e32 v22, v22, v22
	v_mul_f32_e32 v23, v23, v23
	v_cvt_pk_bf16_f32 v34, v20, v21
	v_cvt_pk_bf16_f32 v35, v22, v23
	global_store_dwordx2 v158, v[34:35], s[56:57] sc0 sc1
	v_add_u32_e32 v158, 0x8000, v158
	s_waitcnt lgkmcnt(1)
	v_max_f32_e32 v24, 0, v24
	v_max_f32_e32 v25, 0, v25
	v_max_f32_e32 v26, 0, v26
	v_max_f32_e32 v27, 0, v27
	v_mul_f32_e32 v24, v24, v24
	v_mul_f32_e32 v25, v25, v25
	v_mul_f32_e32 v26, v26, v26
	v_mul_f32_e32 v27, v27, v27
	v_cvt_pk_bf16_f32 v36, v24, v25
	v_cvt_pk_bf16_f32 v37, v26, v27
	global_store_dwordx2 v158, v[36:37], s[56:57] sc0 sc1
	v_add_u32_e32 v158, 0x8000, v158
	s_waitcnt lgkmcnt(0)
	v_max_f32_e32 v28, 0, v28
	v_max_f32_e32 v29, 0, v29
	v_max_f32_e32 v30, 0, v30
	v_max_f32_e32 v31, 0, v31
	v_mul_f32_e32 v28, v28, v28
	v_mul_f32_e32 v29, v29, v29
	v_mul_f32_e32 v30, v30, v30
	v_mul_f32_e32 v31, v31, v31
	v_cvt_pk_bf16_f32 v38, v28, v29
	v_cvt_pk_bf16_f32 v39, v30, v31
	global_store_dwordx2 v158, v[38:39], s[56:57] sc0 sc1
	v_add_u32_e32 v158, 0x8000, v158
	v_mov_b32_e32 v44, 0
	v_mov_b32_e32 v45, 0
	v_mov_b32_e32 v46, 0
	v_mov_b32_e32 v47, 0
	v_mov_b32_e32 v48, 0
	v_mov_b32_e32 v49, 0
	v_mov_b32_e32 v50, 0
	v_mov_b32_e32 v51, 0
	v_mov_b32_e32 v52, 0
	v_mov_b32_e32 v53, 0
	v_mov_b32_e32 v54, 0
	v_mov_b32_e32 v55, 0
	v_mov_b32_e32 v56, 0
	v_mov_b32_e32 v57, 0
	v_mov_b32_e32 v58, 0
	v_mov_b32_e32 v59, 0
	v_mov_b32_e32 v60, 0
	v_mov_b32_e32 v61, 0
	v_mov_b32_e32 v62, 0
	v_mov_b32_e32 v63, 0
	v_mov_b32_e32 v64, 0
	v_mov_b32_e32 v65, 0
	v_mov_b32_e32 v66, 0
	v_mov_b32_e32 v67, 0
	v_mov_b32_e32 v68, 0
	v_mov_b32_e32 v69, 0
	v_mov_b32_e32 v70, 0
	v_mov_b32_e32 v71, 0
	v_mov_b32_e32 v72, 0
	v_mov_b32_e32 v73, 0
	v_mov_b32_e32 v74, 0
	v_mov_b32_e32 v75, 0
	v_mov_b32_e32 v76, 0
	v_mov_b32_e32 v77, 0
	v_mov_b32_e32 v78, 0
	v_mov_b32_e32 v79, 0
	v_mov_b32_e32 v80, 0
	v_mov_b32_e32 v81, 0
	v_mov_b32_e32 v82, 0
	v_mov_b32_e32 v83, 0
	v_mov_b32_e32 v84, 0
	v_mov_b32_e32 v85, 0
	v_mov_b32_e32 v86, 0
	v_mov_b32_e32 v87, 0
	v_mov_b32_e32 v88, 0
	v_mov_b32_e32 v89, 0
	v_mov_b32_e32 v90, 0
	v_mov_b32_e32 v91, 0
	s_mov_b32 s34, 0
	s_add_u32 s35, s35, s52
	s_add_u32 s31, s31, 1
	s_cmp_ge_u32 s31, s30
	s_cbranch_scc1 .Lgm_f1_exit
	s_waitcnt vmcnt(17)
	s_branch .Lgm_f1_rot_a

.Lgm_f2_cnt:
	s_add_u32 s30, s30, 64
	s_add_u32 s4, s4, s52
	s_cmp_lt_u32 s4, s54
	s_cbranch_scc1 .Lgm_f2_cnt
	s_add_u32 s48, s96, 0x3a24000
	s_addc_u32 s49, s97, 0
	s_mul_i32 s4, s36, 0x800000
	s_add_u32 s50, s96, 0x1d80000
	s_addc_u32 s51, s97, 0
	s_add_u32 s50, s50, s4
	s_addc_u32 s51, s51, 0
	v_and_b32_e32 v0, 63, v206
	v_lshrrev_b32_e32 v1, 6, v206
	v_lshrrev_b32_e32 v3, 3, v0
	v_and_b32_e32 v4, 7, v0
	v_readfirstlane_b32 s42, v1
	v_xor_b32_e32 v4, v4, v3
	v_lshl_add_u32 v3, v1, 3, v3
	v_lshlrev_b32_e32 v3, 13, v3
	v_lshl_add_u32 v148, v4, 4, v3
	v_add_u32_e32 v149, 0x80000, v148
	v_add_u32_e32 v150, 0x100000, v148
	v_and_b32_e32 v5, 15, v0
	v_lshrrev_b32_e32 v6, 4, v0
	v_and_b32_e32 v7, 7, v5
	v_xor_b32_e32 v7, v7, v6
	v_lshlrev_b32_e32 v7, 4, v7
	v_lshrrev_b32_e32 v8, 1, v1
	v_and_b32_e32 v9, 1, v1
	v_mul_u32_u24_e32 v10, 48, v8
	v_add_u32_e32 v11, v10, v5
	v_lshl_add_u32 v151, v11, 7, v7
	v_xor_b32_e32 v152, 64, v151
	v_lshl_add_u32 v11, v9, 6, v5
	v_lshl_add_u32 v153, v11, 7, v7
	v_add_u32_e32 v153, 0x6000, v153
	v_xor_b32_e32 v154, 64, v153
	s_mul_i32 s5, s42, 4352
	s_mov_b32 s6, 0x1ec10
	s_cmp_lt_u32 s42, 4
	s_cselect_b32 s6, 0x1e000, s6
	s_add_u32 s5, s5, s6
	s_mov_b32 s43, s5
	v_mul_u32_u24_e32 v11, 1088, v6
	v_lshl_add_u32 v11, v5, 2, v11
	v_add_u32_e32 v155, s5, v11
	v_mul_u32_u24_e32 v11, 272, v6
	v_lshl_add_u32 v11, v5, 4, v11
	v_add_u32_e32 v156, s5, v11
	v_add_u32_e32 v11, v10, v6
	v_lshlrev_b32_e32 v12, 6, v9
	v_lshl_add_u32 v12, v5, 2, v12
	s_mov_b32 s4, 0x1000
	v_mul_lo_u32 v13, v11, s4
	v_lshl_add_u32 v157, v12, 2, v13
	v_mov_b32_e32 v159, v11
	v_lshlrev_b32_e32 v160, 2, v12
	s_lshl_b32 s42, s42, 10
	v_mov_b32_e32 v44, 0
	v_mov_b32_e32 v45, 0
	v_mov_b32_e32 v46, 0
	v_mov_b32_e32 v47, 0
	v_mov_b32_e32 v48, 0
	v_mov_b32_e32 v49, 0
	v_mov_b32_e32 v50, 0
	v_mov_b32_e32 v51, 0
	v_mov_b32_e32 v52, 0
	v_mov_b32_e32 v53, 0
	v_mov_b32_e32 v54, 0
	v_mov_b32_e32 v55, 0
	v_mov_b32_e32 v56, 0
	v_mov_b32_e32 v57, 0
	v_mov_b32_e32 v58, 0
	v_mov_b32_e32 v59, 0
	v_mov_b32_e32 v60, 0
	v_mov_b32_e32 v61, 0
	v_mov_b32_e32 v62, 0
	v_mov_b32_e32 v63, 0
	v_mov_b32_e32 v64, 0
	v_mov_b32_e32 v65, 0
	v_mov_b32_e32 v66, 0
	v_mov_b32_e32 v67, 0
	v_mov_b32_e32 v68, 0
	v_mov_b32_e32 v69, 0
	v_mov_b32_e32 v70, 0
	v_mov_b32_e32 v71, 0
	v_mov_b32_e32 v72, 0
	v_mov_b32_e32 v73, 0
	v_mov_b32_e32 v74, 0
	v_mov_b32_e32 v75, 0
	v_mov_b32_e32 v76, 0
	v_mov_b32_e32 v77, 0
	v_mov_b32_e32 v78, 0
	v_mov_b32_e32 v79, 0
	v_mov_b32_e32 v80, 0
	v_mov_b32_e32 v81, 0
	v_mov_b32_e32 v82, 0
	v_mov_b32_e32 v83, 0
	v_mov_b32_e32 v84, 0
	v_mov_b32_e32 v85, 0
	v_mov_b32_e32 v86, 0
	v_mov_b32_e32 v87, 0
	v_mov_b32_e32 v88, 0
	v_mov_b32_e32 v89, 0
	v_mov_b32_e32 v90, 0
	v_mov_b32_e32 v91, 0
	s_mov_b32 s31, 0
	s_mov_b32 s34, 0
	s_mov_b32 s35, s53
	s_mov_b32 s38, s53
	s_mov_b32 s39, 0
	s_mov_b32 s40, 0
	s_mov_b32 s41, s42
	s_and_b32 s4, s38, 31
	s_mul_i32 s4, s4, 0x180000
	s_add_u32 s44, s48, s4
	s_addc_u32 s45, s49, 0
	s_lshr_b32 s4, s38, 5
	s_mul_i32 s4, s4, 0x100000
	s_add_u32 s46, s50, s4
	s_addc_u32 s47, s51, 0
	s_add_u32 m0, s41, 0x0
	s_nop 0
	global_load_lds_dwordx4 v148, s[44:45]
	s_add_u32 m0, s41, 0x2000
	s_nop 0
	global_load_lds_dwordx4 v149, s[44:45]
	s_add_u32 m0, s41, 0x4000
	s_nop 0
	global_load_lds_dwordx4 v150, s[44:45]
	s_add_u32 m0, s41, 0x6000
	s_nop 0
	global_load_lds_dwordx4 v148, s[46:47]
	s_add_u32 m0, s41, 0x8000
	s_nop 0
	global_load_lds_dwordx4 v149, s[46:47]
	s_add_u32 s39, s39, 1
	s_add_u32 s44, s44, 0x80
	s_addc_u32 s45, s45, 0
	s_add_u32 s46, s46, 0x80
	s_addc_u32 s47, s47, 0
	s_cmp_lt_u32 s39, 64
	s_cbranch_scc1 .Lgm_f2_dadv1
	s_mov_b32 s39, 0
	s_add_u32 s4, s38, s52
	s_cmp_lt_u32 s4, s54
	s_cselect_b32 s38, s4, s38
	s_and_b32 s4, s38, 31
	s_mul_i32 s4, s4, 0x180000
	s_add_u32 s44, s48, s4
	s_addc_u32 s45, s49, 0
	s_lshr_b32 s4, s38, 5
	s_mul_i32 s4, s4, 0x100000
	s_add_u32 s46, s50, s4
	s_addc_u32 s47, s51, 0

.Lgm_f2_dadv3:
	ds_read_b128 v[120:123], v152 offset:0
	ds_read_b128 v[124:127], v152 offset:2048
	ds_read_b128 v[128:131], v152 offset:4096
	ds_read_b128 v[132:135], v154 offset:0
	ds_read_b128 v[136:139], v154 offset:2048
	ds_read_b128 v[140:143], v154 offset:4096
	ds_read_b128 v[144:147], v154 offset:6144
	s_waitcnt lgkmcnt(10)
	v_mfma_f32_16x16x32_bf16 v[44:47], v[92:95], v[104:107], v[44:47]
	v_mfma_f32_16x16x32_bf16 v[60:63], v[96:99], v[104:107], v[60:63]
	v_mfma_f32_16x16x32_bf16 v[76:79], v[100:103], v[104:107], v[76:79]
	s_waitcnt lgkmcnt(9)
	v_mfma_f32_16x16x32_bf16 v[48:51], v[92:95], v[108:111], v[48:51]
	v_mfma_f32_16x16x32_bf16 v[64:67], v[96:99], v[108:111], v[64:67]
	v_mfma_f32_16x16x32_bf16 v[80:83], v[100:103], v[108:111], v[80:83]
	s_waitcnt lgkmcnt(8)
	v_mfma_f32_16x16x32_bf16 v[52:55], v[92:95], v[112:115], v[52:55]
	v_mfma_f32_16x16x32_bf16 v[68:71], v[96:99], v[112:115], v[68:71]
	v_mfma_f32_16x16x32_bf16 v[84:87], v[100:103], v[112:115], v[84:87]
	s_waitcnt lgkmcnt(7)
	v_mfma_f32_16x16x32_bf16 v[56:59], v[92:95], v[116:119], v[56:59]
	v_mfma_f32_16x16x32_bf16 v[72:75], v[96:99], v[116:119], v[72:75]
	v_mfma_f32_16x16x32_bf16 v[88:91], v[100:103], v[116:119], v[88:91]
	s_waitcnt lgkmcnt(0)
	s_add_u32 s34, s34, 1
	s_cmp_lt_u32 s34, 64
	s_cbranch_scc1 .Lgm_f2_next_a
	v_mfma_f32_16x16x32_bf16 v[44:47], v[120:123], v[132:135], v[44:47]
	v_mfma_f32_16x16x32_bf16 v[60:63], v[124:127], v[132:135], v[60:63]
	v_mfma_f32_16x16x32_bf16 v[76:79], v[128:131], v[132:135], v[76:79]
	v_mfma_f32_16x16x32_bf16 v[48:51], v[120:123], v[136:139], v[48:51]
	v_mfma_f32_16x16x32_bf16 v[64:67], v[124:127], v[136:139], v[64:67]
	v_mfma_f32_16x16x32_bf16 v[80:83], v[128:131], v[136:139], v[80:83]
	v_mfma_f32_16x16x32_bf16 v[52:55], v[120:123], v[140:143], v[52:55]
	v_mfma_f32_16x16x32_bf16 v[68:71], v[124:127], v[140:143], v[68:71]
	v_mfma_f32_16x16x32_bf16 v[84:87], v[128:131], v[140:143], v[84:87]
	v_mfma_f32_16x16x32_bf16 v[56:59], v[120:123], v[144:147], v[56:59]
	v_mfma_f32_16x16x32_bf16 v[72:75], v[124:127], v[144:147], v[72:75]
	v_mfma_f32_16x16x32_bf16 v[88:91], v[128:131], v[144:147], v[88:91]
	s_and_b32 s6, s35, 31
	s_mul_i32 s6, s6, 192
	s_lshr_b32 s7, s35, 5
	s_lshl_b32 s7, s7, 7
	s_nop 7
	s_mul_i32 s4, s6, 0x1000
	s_lshl_b32 s5, s7, 2
	s_add_u32 s4, s4, s5
	v_add_u32_e32 v158, s4, v157
	v_add_u32_e32 v161, s6, v159
	v_lshl_add_u32 v162, s7, 2, v160
	s_sub_i32 s4, s6, 0xc00
	s_max_i32 s4, s4, 0
	s_lshr_b32 s4, s4, 10
	s_add_i32 s5, s6, -2881
	s_max_i32 s5, s5, 0
	s_lshr_b32 s5, s5, 10
	s_movk_i32 s7, 0x1400
	s_cmp_eq_u32 s4, 0
	s_cselect_b32 s7, 0x1000, s7
	s_mul_i32 s4, s4, 0x6000
	s_mul_i32 s5, s5, 0x6000
	v_mov_b32_e32 v163, v158
	v_add_u32_e32 v164, 0, v161
	v_cmp_gt_u32_e32 vcc, 0x1000, v164
	v_mov_b32_e32 v0, s98
	v_mov_b32_e32 v1, s99
	v_mov_b32_e32 v3, s58
	v_cndmask_b32_e32 v0, v0, v3, vcc
	v_mov_b32_e32 v3, s59
	v_cndmask_b32_e32 v1, v1, v3, vcc
	v_add_co_u32_e32 v0, vcc, v0, v163
	s_nop 1
	v_addc_co_u32_e32 v1, vcc, 0, v1, vcc
	global_load_dwordx4 v[92:95], v[0:1], off
	v_add_u32_e32 v163, 0x4000, v163
	v_add_u32_e32 v164, 4, v161
	v_cmp_gt_u32_e32 vcc, 0x1000, v164
	v_mov_b32_e32 v0, s98
	v_mov_b32_e32 v1, s99
	v_mov_b32_e32 v3, s58
	v_cndmask_b32_e32 v0, v0, v3, vcc
	v_mov_b32_e32 v3, s59
	v_cndmask_b32_e32 v1, v1, v3, vcc
	v_add_co_u32_e32 v0, vcc, v0, v163
	s_nop 1
	v_addc_co_u32_e32 v1, vcc, 0, v1, vcc
	global_load_dwordx4 v[96:99], v[0:1], off
	v_add_u32_e32 v163, 0x4000, v163
	v_add_u32_e32 v164, 8, v161
	v_cmp_gt_u32_e32 vcc, 0x1000, v164
	v_mov_b32_e32 v0, s98
	v_mov_b32_e32 v1, s99
	v_mov_b32_e32 v3, s58
	v_cndmask_b32_e32 v0, v0, v3, vcc
	v_mov_b32_e32 v3, s59
	v_cndmask_b32_e32 v1, v1, v3, vcc
	v_add_co_u32_e32 v0, vcc, v0, v163
	s_nop 1
	v_addc_co_u32_e32 v1, vcc, 0, v1, vcc
	global_load_dwordx4 v[100:103], v[0:1], off
	v_add_u32_e32 v163, 0x4000, v163
	v_add_u32_e32 v164, 12, v161
	v_cmp_gt_u32_e32 vcc, 0x1000, v164
	v_mov_b32_e32 v0, s98
	v_mov_b32_e32 v1, s99
	v_mov_b32_e32 v3, s58
	v_cndmask_b32_e32 v0, v0, v3, vcc
	v_mov_b32_e32 v3, s59
	v_cndmask_b32_e32 v1, v1, v3, vcc
	v_add_co_u32_e32 v0, vcc, v0, v163
	s_nop 1
	v_addc_co_u32_e32 v1, vcc, 0, v1, vcc
	global_load_dwordx4 v[104:107], v[0:1], off
	v_add_u32_e32 v163, 0x4000, v163
	v_add_u32_e32 v164, 16, v161
	v_cmp_gt_u32_e32 vcc, 0x1000, v164
	v_mov_b32_e32 v0, s98
	v_mov_b32_e32 v1, s99
	v_mov_b32_e32 v3, s58
	v_cndmask_b32_e32 v0, v0, v3, vcc
	v_mov_b32_e32 v3, s59
	v_cndmask_b32_e32 v1, v1, v3, vcc
	v_add_co_u32_e32 v0, vcc, v0, v163
	s_nop 1
	v_addc_co_u32_e32 v1, vcc, 0, v1, vcc
	global_load_dwordx4 v[108:111], v[0:1], off
	v_add_u32_e32 v163, 0x4000, v163
	v_add_u32_e32 v164, 20, v161
	v_cmp_gt_u32_e32 vcc, 0x1000, v164
	v_mov_b32_e32 v0, s98
	v_mov_b32_e32 v1, s99
	v_mov_b32_e32 v3, s58
	v_cndmask_b32_e32 v0, v0, v3, vcc
	v_mov_b32_e32 v3, s59
	v_cndmask_b32_e32 v1, v1, v3, vcc
	v_add_co_u32_e32 v0, vcc, v0, v163
	s_nop 1
	v_addc_co_u32_e32 v1, vcc, 0, v1, vcc
	global_load_dwordx4 v[112:115], v[0:1], off
	v_add_u32_e32 v163, 0x4000, v163
	v_add_u32_e32 v164, 24, v161
	v_cmp_gt_u32_e32 vcc, 0x1000, v164
	v_mov_b32_e32 v0, s98
	v_mov_b32_e32 v1, s99
	v_mov_b32_e32 v3, s58
	v_cndmask_b32_e32 v0, v0, v3, vcc
	v_mov_b32_e32 v3, s59
	v_cndmask_b32_e32 v1, v1, v3, vcc
	v_add_co_u32_e32 v0, vcc, v0, v163
	s_nop 1
	v_addc_co_u32_e32 v1, vcc, 0, v1, vcc
	global_load_dwordx4 v[116:119], v[0:1], off
	v_add_u32_e32 v163, 0x4000, v163
	v_add_u32_e32 v164, 28, v161
	v_cmp_gt_u32_e32 vcc, 0x1000, v164
	v_mov_b32_e32 v0, s98
	v_mov_b32_e32 v1, s99
	v_mov_b32_e32 v3, s58
	v_cndmask_b32_e32 v0, v0, v3, vcc
	v_mov_b32_e32 v3, s59
	v_cndmask_b32_e32 v1, v1, v3, vcc
	v_add_co_u32_e32 v0, vcc, v0, v163
	s_nop 1
	v_addc_co_u32_e32 v1, vcc, 0, v1, vcc
	global_load_dwordx4 v[120:123], v[0:1], off
	v_add_u32_e32 v163, 0x4000, v163
	v_add_u32_e32 v164, 32, v161
	v_cmp_gt_u32_e32 vcc, 0x1000, v164
	v_mov_b32_e32 v0, s98
	v_mov_b32_e32 v1, s99
	v_mov_b32_e32 v3, s58
	v_cndmask_b32_e32 v0, v0, v3, vcc
	v_mov_b32_e32 v3, s59
	v_cndmask_b32_e32 v1, v1, v3, vcc
	v_add_co_u32_e32 v0, vcc, v0, v163
	s_nop 1
	v_addc_co_u32_e32 v1, vcc, 0, v1, vcc
	global_load_dwordx4 v[124:127], v[0:1], off
	v_add_u32_e32 v163, 0x4000, v163
	v_add_u32_e32 v164, 36, v161
	v_cmp_gt_u32_e32 vcc, 0x1000, v164
	v_mov_b32_e32 v0, s98
	v_mov_b32_e32 v1, s99
	v_mov_b32_e32 v3, s58
	v_cndmask_b32_e32 v0, v0, v3, vcc
	v_mov_b32_e32 v3, s59
	v_cndmask_b32_e32 v1, v1, v3, vcc
	v_add_co_u32_e32 v0, vcc, v0, v163
	s_nop 1
	v_addc_co_u32_e32 v1, vcc, 0, v1, vcc
	global_load_dwordx4 v[128:131], v[0:1], off
	v_add_u32_e32 v163, 0x4000, v163
	v_add_u32_e32 v164, 40, v161
	v_cmp_gt_u32_e32 vcc, 0x1000, v164
	v_mov_b32_e32 v0, s98
	v_mov_b32_e32 v1, s99
	v_mov_b32_e32 v3, s58
	v_cndmask_b32_e32 v0, v0, v3, vcc
	v_mov_b32_e32 v3, s59
	v_cndmask_b32_e32 v1, v1, v3, vcc
	v_add_co_u32_e32 v0, vcc, v0, v163
	s_nop 1
	v_addc_co_u32_e32 v1, vcc, 0, v1, vcc
	global_load_dwordx4 v[132:135], v[0:1], off
	v_add_u32_e32 v163, 0x4000, v163
	v_add_u32_e32 v164, 44, v161
	v_cmp_gt_u32_e32 vcc, 0x1000, v164
	v_mov_b32_e32 v0, s98
	v_mov_b32_e32 v1, s99
	v_mov_b32_e32 v3, s58
	v_cndmask_b32_e32 v0, v0, v3, vcc
	v_mov_b32_e32 v3, s59
	v_cndmask_b32_e32 v1, v1, v3, vcc
	v_add_co_u32_e32 v0, vcc, v0, v163
	s_nop 1
	v_addc_co_u32_e32 v1, vcc, 0, v1, vcc
	global_load_dwordx4 v[136:139], v[0:1], off
	v_add_u32_e32 v163, 0x4000, v163
	v_add_u32_e32 v164, s4, v162
	global_load_dwordx4 v[4:7], v164, s[100:101]
	v_add_u32_e32 v164, s5, v162
	global_load_dwordx4 v[8:11], v164, s[100:101]
	ds_write_b32 v155, v44 offset:0
	ds_write_b32 v155, v45 offset:272
	ds_write_b32 v155, v46 offset:544
	ds_write_b32 v155, v47 offset:816
	ds_write_b32 v155, v48 offset:64
	ds_write_b32 v155, v49 offset:336
	ds_write_b32 v155, v50 offset:608
	ds_write_b32 v155, v51 offset:880
	ds_write_b32 v155, v52 offset:128
	ds_write_b32 v155, v53 offset:400
	ds_write_b32 v155, v54 offset:672
	ds_write_b32 v155, v55 offset:944
	ds_write_b32 v155, v56 offset:192
	ds_write_b32 v155, v57 offset:464
	ds_write_b32 v155, v58 offset:736
	ds_write_b32 v155, v59 offset:1008
	s_waitcnt lgkmcnt(0)
	ds_read_b128 v[16:19], v156 offset:0
	ds_read_b128 v[20:23], v156 offset:1088
	ds_read_b128 v[24:27], v156 offset:2176
	ds_read_b128 v[28:31], v156 offset:3264
	v_add_u32_e32 v164, 0, v161
	v_cmp_le_u32_e32 vcc, s7, v164
	s_waitcnt vmcnt(0)
	s_waitcnt lgkmcnt(3)
	v_cndmask_b32_e32 v12, v4, v8, vcc
	v_cndmask_b32_e32 v13, v5, v9, vcc
	v_cndmask_b32_e32 v14, v6, v10, vcc
	v_cndmask_b32_e32 v15, v7, v11, vcc
	v_fmac_f32_e32 v92, v12, v16
	v_fmac_f32_e32 v93, v13, v17
	v_fmac_f32_e32 v94, v14, v18
	v_fmac_f32_e32 v95, v15, v19
	global_store_dwordx4 v158, v[92:95], s[56:57] sc0 sc1
	v_add_u32_e32 v158, 0x4000, v158
	v_add_u32_e32 v164, 4, v161
	v_cmp_le_u32_e32 vcc, s7, v164
	s_waitcnt vmcnt(1)
	s_waitcnt lgkmcnt(2)
	v_cndmask_b32_e32 v12, v4, v8, vcc
	v_cndmask_b32_e32 v13, v5, v9, vcc
	v_cndmask_b32_e32 v14, v6, v10, vcc
	v_cndmask_b32_e32 v15, v7, v11, vcc
	v_fmac_f32_e32 v96, v12, v20
	v_fmac_f32_e32 v97, v13, v21
	v_fmac_f32_e32 v98, v14, v22
	v_fmac_f32_e32 v99, v15, v23
	global_store_dwordx4 v158, v[96:99], s[56:57] sc0 sc1
	v_add_u32_e32 v158, 0x4000, v158
	v_add_u32_e32 v164, 8, v161
	v_cmp_le_u32_e32 vcc, s7, v164
	s_waitcnt vmcnt(2)
	s_waitcnt lgkmcnt(1)
	v_cndmask_b32_e32 v12, v4, v8, vcc
	v_cndmask_b32_e32 v13, v5, v9, vcc
	v_cndmask_b32_e32 v14, v6, v10, vcc
	v_cndmask_b32_e32 v15, v7, v11, vcc
	v_fmac_f32_e32 v100, v12, v24
	v_fmac_f32_e32 v101, v13, v25
	v_fmac_f32_e32 v102, v14, v26
	v_fmac_f32_e32 v103, v15, v27
	global_store_dwordx4 v158, v[100:103], s[56:57] sc0 sc1
	v_add_u32_e32 v158, 0x4000, v158
	v_add_u32_e32 v164, 12, v161
	v_cmp_le_u32_e32 vcc, s7, v164
	s_waitcnt vmcnt(3)
	s_waitcnt lgkmcnt(0)
	v_cndmask_b32_e32 v12, v4, v8, vcc
	v_cndmask_b32_e32 v13, v5, v9, vcc
	v_cndmask_b32_e32 v14, v6, v10, vcc
	v_cndmask_b32_e32 v15, v7, v11, vcc
	v_fmac_f32_e32 v104, v12, v28
	v_fmac_f32_e32 v105, v13, v29
	v_fmac_f32_e32 v106, v14, v30
	v_fmac_f32_e32 v107, v15, v31
	global_store_dwordx4 v158, v[104:107], s[56:57] sc0 sc1
	v_add_u32_e32 v158, 0x4000, v158
	ds_write_b32 v155, v60 offset:0
	ds_write_b32 v155, v61 offset:272
	ds_write_b32 v155, v62 offset:544
	ds_write_b32 v155, v63 offset:816
	ds_write_b32 v155, v64 offset:64
	ds_write_b32 v155, v65 offset:336
	ds_write_b32 v155, v66 offset:608
	ds_write_b32 v155, v67 offset:880
	ds_write_b32 v155, v68 offset:128
	ds_write_b32 v155, v69 offset:400
	ds_write_b32 v155, v70 offset:672
	ds_write_b32 v155, v71 offset:944
	ds_write_b32 v155, v72 offset:192
	ds_write_b32 v155, v73 offset:464
	ds_write_b32 v155, v74 offset:736
	ds_write_b32 v155, v75 offset:1008
	s_waitcnt lgkmcnt(0)
	ds_read_b128 v[16:19], v156 offset:0
	ds_read_b128 v[20:23], v156 offset:1088
	ds_read_b128 v[24:27], v156 offset:2176
	ds_read_b128 v[28:31], v156 offset:3264
	v_add_u32_e32 v164, 16, v161
	v_cmp_le_u32_e32 vcc, s7, v164
	s_waitcnt vmcnt(4)
	s_waitcnt lgkmcnt(3)
	v_cndmask_b32_e32 v12, v4, v8, vcc
	v_cndmask_b32_e32 v13, v5, v9, vcc
	v_cndmask_b32_e32 v14, v6, v10, vcc
	v_cndmask_b32_e32 v15, v7, v11, vcc
	v_fmac_f32_e32 v108, v12, v16
	v_fmac_f32_e32 v109, v13, v17
	v_fmac_f32_e32 v110, v14, v18
	v_fmac_f32_e32 v111, v15, v19
	global_store_dwordx4 v158, v[108:111], s[56:57] sc0 sc1
	v_add_u32_e32 v158, 0x4000, v158
	v_add_u32_e32 v164, 20, v161
	v_cmp_le_u32_e32 vcc, s7, v164
	s_waitcnt vmcnt(5)
	s_waitcnt lgkmcnt(2)
	v_cndmask_b32_e32 v12, v4, v8, vcc
	v_cndmask_b32_e32 v13, v5, v9, vcc
	v_cndmask_b32_e32 v14, v6, v10, vcc
	v_cndmask_b32_e32 v15, v7, v11, vcc
	v_fmac_f32_e32 v112, v12, v20
	v_fmac_f32_e32 v113, v13, v21
	v_fmac_f32_e32 v114, v14, v22
	v_fmac_f32_e32 v115, v15, v23
	global_store_dwordx4 v158, v[112:115], s[56:57] sc0 sc1
	v_add_u32_e32 v158, 0x4000, v158
	v_add_u32_e32 v164, 24, v161
	v_cmp_le_u32_e32 vcc, s7, v164
	s_waitcnt vmcnt(6)
	s_waitcnt lgkmcnt(1)
	v_cndmask_b32_e32 v12, v4, v8, vcc
	v_cndmask_b32_e32 v13, v5, v9, vcc
	v_cndmask_b32_e32 v14, v6, v10, vcc
	v_cndmask_b32_e32 v15, v7, v11, vcc
	v_fmac_f32_e32 v116, v12, v24
	v_fmac_f32_e32 v117, v13, v25
	v_fmac_f32_e32 v118, v14, v26
	v_fmac_f32_e32 v119, v15, v27
	global_store_dwordx4 v158, v[116:119], s[56:57] sc0 sc1
	v_add_u32_e32 v158, 0x4000, v158
	v_add_u32_e32 v164, 28, v161
	v_cmp_le_u32_e32 vcc, s7, v164
	s_waitcnt vmcnt(7)
	s_waitcnt lgkmcnt(0)
	v_cndmask_b32_e32 v12, v4, v8, vcc
	v_cndmask_b32_e32 v13, v5, v9, vcc
	v_cndmask_b32_e32 v14, v6, v10, vcc
	v_cndmask_b32_e32 v15, v7, v11, vcc
	v_fmac_f32_e32 v120, v12, v28
	v_fmac_f32_e32 v121, v13, v29
	v_fmac_f32_e32 v122, v14, v30
	v_fmac_f32_e32 v123, v15, v31
	global_store_dwordx4 v158, v[120:123], s[56:57] sc0 sc1
	v_add_u32_e32 v158, 0x4000, v158
	ds_write_b32 v155, v76 offset:0
	ds_write_b32 v155, v77 offset:272
	ds_write_b32 v155, v78 offset:544
	ds_write_b32 v155, v79 offset:816
	ds_write_b32 v155, v80 offset:64
	ds_write_b32 v155, v81 offset:336
	ds_write_b32 v155, v82 offset:608
	ds_write_b32 v155, v83 offset:880
	ds_write_b32 v155, v84 offset:128
	ds_write_b32 v155, v85 offset:400
	ds_write_b32 v155, v86 offset:672
	ds_write_b32 v155, v87 offset:944
	ds_write_b32 v155, v88 offset:192
	ds_write_b32 v155, v89 offset:464
	ds_write_b32 v155, v90 offset:736
	ds_write_b32 v155, v91 offset:1008
	s_waitcnt lgkmcnt(0)
	ds_read_b128 v[16:19], v156 offset:0
	ds_read_b128 v[20:23], v156 offset:1088
	ds_read_b128 v[24:27], v156 offset:2176
	ds_read_b128 v[28:31], v156 offset:3264
	v_add_u32_e32 v164, 32, v161
	v_cmp_le_u32_e32 vcc, s7, v164
	s_waitcnt vmcnt(8)
	s_waitcnt lgkmcnt(3)
	v_cndmask_b32_e32 v12, v4, v8, vcc
	v_cndmask_b32_e32 v13, v5, v9, vcc
	v_cndmask_b32_e32 v14, v6, v10, vcc
	v_cndmask_b32_e32 v15, v7, v11, vcc
	v_fmac_f32_e32 v124, v12, v16
	v_fmac_f32_e32 v125, v13, v17
	v_fmac_f32_e32 v126, v14, v18
	v_fmac_f32_e32 v127, v15, v19
	global_store_dwordx4 v158, v[124:127], s[56:57] sc0 sc1
	v_add_u32_e32 v158, 0x4000, v158
	v_add_u32_e32 v164, 36, v161
	v_cmp_le_u32_e32 vcc, s7, v164
	s_waitcnt vmcnt(9)
	s_waitcnt lgkmcnt(2)
	v_cndmask_b32_e32 v12, v4, v8, vcc
	v_cndmask_b32_e32 v13, v5, v9, vcc
	v_cndmask_b32_e32 v14, v6, v10, vcc
	v_cndmask_b32_e32 v15, v7, v11, vcc
	v_fmac_f32_e32 v128, v12, v20
	v_fmac_f32_e32 v129, v13, v21
	v_fmac_f32_e32 v130, v14, v22
	v_fmac_f32_e32 v131, v15, v23
	global_store_dwordx4 v158, v[128:131], s[56:57] sc0 sc1
	v_add_u32_e32 v158, 0x4000, v158
	v_add_u32_e32 v164, 40, v161
	v_cmp_le_u32_e32 vcc, s7, v164
	s_waitcnt vmcnt(10)
	s_waitcnt lgkmcnt(1)
	v_cndmask_b32_e32 v12, v4, v8, vcc
	v_cndmask_b32_e32 v13, v5, v9, vcc
	v_cndmask_b32_e32 v14, v6, v10, vcc
	v_cndmask_b32_e32 v15, v7, v11, vcc
	v_fmac_f32_e32 v132, v12, v24
	v_fmac_f32_e32 v133, v13, v25
	v_fmac_f32_e32 v134, v14, v26
	v_fmac_f32_e32 v135, v15, v27
	global_store_dwordx4 v158, v[132:135], s[56:57] sc0 sc1
	v_add_u32_e32 v158, 0x4000, v158
	v_add_u32_e32 v164, 44, v161
	v_cmp_le_u32_e32 vcc, s7, v164
	s_waitcnt vmcnt(11)
	s_waitcnt lgkmcnt(0)
	v_cndmask_b32_e32 v12, v4, v8, vcc
	v_cndmask_b32_e32 v13, v5, v9, vcc
	v_cndmask_b32_e32 v14, v6, v10, vcc
	v_cndmask_b32_e32 v15, v7, v11, vcc
	v_fmac_f32_e32 v136, v12, v28
	v_fmac_f32_e32 v137, v13, v29
	v_fmac_f32_e32 v138, v14, v30
	v_fmac_f32_e32 v139, v15, v31
	global_store_dwordx4 v158, v[136:139], s[56:57] sc0 sc1
	v_add_u32_e32 v158, 0x4000, v158
	v_mov_b32_e32 v44, 0
	v_mov_b32_e32 v45, 0
	v_mov_b32_e32 v46, 0
	v_mov_b32_e32 v47, 0
	v_mov_b32_e32 v48, 0
	v_mov_b32_e32 v49, 0
	v_mov_b32_e32 v50, 0
	v_mov_b32_e32 v51, 0
	v_mov_b32_e32 v52, 0
	v_mov_b32_e32 v53, 0
	v_mov_b32_e32 v54, 0
	v_mov_b32_e32 v55, 0
	v_mov_b32_e32 v56, 0
	v_mov_b32_e32 v57, 0
	v_mov_b32_e32 v58, 0
	v_mov_b32_e32 v59, 0
	v_mov_b32_e32 v60, 0
	v_mov_b32_e32 v61, 0
	v_mov_b32_e32 v62, 0
	v_mov_b32_e32 v63, 0
	v_mov_b32_e32 v64, 0
	v_mov_b32_e32 v65, 0
	v_mov_b32_e32 v66, 0
	v_mov_b32_e32 v67, 0
	v_mov_b32_e32 v68, 0
	v_mov_b32_e32 v69, 0
	v_mov_b32_e32 v70, 0
	v_mov_b32_e32 v71, 0
	v_mov_b32_e32 v72, 0
	v_mov_b32_e32 v73, 0
	v_mov_b32_e32 v74, 0
	v_mov_b32_e32 v75, 0
	v_mov_b32_e32 v76, 0
	v_mov_b32_e32 v77, 0
	v_mov_b32_e32 v78, 0
	v_mov_b32_e32 v79, 0
	v_mov_b32_e32 v80, 0
	v_mov_b32_e32 v81, 0
	v_mov_b32_e32 v82, 0
	v_mov_b32_e32 v83, 0
	v_mov_b32_e32 v84, 0
	v_mov_b32_e32 v85, 0
	v_mov_b32_e32 v86, 0
	v_mov_b32_e32 v87, 0
	v_mov_b32_e32 v88, 0
	v_mov_b32_e32 v89, 0
	v_mov_b32_e32 v90, 0
	v_mov_b32_e32 v91, 0
	s_mov_b32 s34, 0
	s_add_u32 s35, s35, s52
	s_add_u32 s31, s31, 1
	s_cmp_ge_u32 s31, s30
	s_cbranch_scc1 .Lgm_f2_exit
	s_waitcnt vmcnt(17)
	s_branch .Lgm_f2_rot_a

.Lgm_wo_cnt:
	s_add_u32 s30, s30, 16
	s_add_u32 s4, s4, s52
	s_cmp_lt_u32 s4, s54
	s_cbranch_scc1 .Lgm_wo_cnt
	s_add_u32 s48, s96, 0x7084000
	s_addc_u32 s49, s97, 0
	s_mul_i32 s4, s36, 0x200000
	s_add_u32 s50, s96, 0x980000
	s_addc_u32 s51, s97, 0
	s_add_u32 s50, s50, s4
	s_addc_u32 s51, s51, 0
	v_and_b32_e32 v0, 63, v206
	v_lshrrev_b32_e32 v1, 6, v206
	v_lshrrev_b32_e32 v3, 3, v0
	v_and_b32_e32 v4, 7, v0
	v_readfirstlane_b32 s42, v1
	v_xor_b32_e32 v4, v4, v3
	v_lshl_add_u32 v3, v1, 3, v3
	v_lshlrev_b32_e32 v3, 11, v3
	v_lshl_add_u32 v148, v4, 4, v3
	v_add_u32_e32 v149, 0x20000, v148
	v_add_u32_e32 v150, 0x40000, v148
	v_and_b32_e32 v5, 15, v0
	v_lshrrev_b32_e32 v6, 4, v0
	v_and_b32_e32 v7, 7, v5
	v_xor_b32_e32 v7, v7, v6
	v_lshlrev_b32_e32 v7, 4, v7
	v_lshrrev_b32_e32 v8, 1, v1
	v_and_b32_e32 v9, 1, v1
	v_mul_u32_u24_e32 v10, 48, v8
	v_add_u32_e32 v11, v10, v5
	v_lshl_add_u32 v151, v11, 7, v7
	v_xor_b32_e32 v152, 64, v151
	v_lshl_add_u32 v11, v9, 6, v5
	v_lshl_add_u32 v153, v11, 7, v7
	v_add_u32_e32 v153, 0x6000, v153
	v_xor_b32_e32 v154, 64, v153
	s_mul_i32 s5, s42, 4352
	s_mov_b32 s6, 0x1ec10
	s_cmp_lt_u32 s42, 4
	s_cselect_b32 s6, 0x1e000, s6
	s_add_u32 s5, s5, s6
	s_mov_b32 s43, s5
	v_mul_u32_u24_e32 v11, 1088, v6
	v_lshl_add_u32 v11, v5, 2, v11
	v_add_u32_e32 v155, s5, v11
	v_mul_u32_u24_e32 v11, 272, v6
	v_lshl_add_u32 v11, v5, 4, v11
	v_add_u32_e32 v156, s5, v11
	v_add_u32_e32 v11, v10, v6
	v_lshlrev_b32_e32 v12, 6, v9
	v_lshl_add_u32 v12, v5, 2, v12
	s_mov_b32 s4, 0x1000
	v_mul_lo_u32 v13, v11, s4
	v_lshl_add_u32 v157, v12, 2, v13
	v_mov_b32_e32 v159, v11
	v_lshlrev_b32_e32 v160, 2, v12
	s_lshl_b32 s42, s42, 10
	v_mov_b32_e32 v44, 0
	v_mov_b32_e32 v45, 0
	v_mov_b32_e32 v46, 0
	v_mov_b32_e32 v47, 0
	v_mov_b32_e32 v48, 0
	v_mov_b32_e32 v49, 0
	v_mov_b32_e32 v50, 0
	v_mov_b32_e32 v51, 0
	v_mov_b32_e32 v52, 0
	v_mov_b32_e32 v53, 0
	v_mov_b32_e32 v54, 0
	v_mov_b32_e32 v55, 0
	v_mov_b32_e32 v56, 0
	v_mov_b32_e32 v57, 0
	v_mov_b32_e32 v58, 0
	v_mov_b32_e32 v59, 0
	v_mov_b32_e32 v60, 0
	v_mov_b32_e32 v61, 0
	v_mov_b32_e32 v62, 0
	v_mov_b32_e32 v63, 0
	v_mov_b32_e32 v64, 0
	v_mov_b32_e32 v65, 0
	v_mov_b32_e32 v66, 0
	v_mov_b32_e32 v67, 0
	v_mov_b32_e32 v68, 0
	v_mov_b32_e32 v69, 0
	v_mov_b32_e32 v70, 0
	v_mov_b32_e32 v71, 0
	v_mov_b32_e32 v72, 0
	v_mov_b32_e32 v73, 0
	v_mov_b32_e32 v74, 0
	v_mov_b32_e32 v75, 0
	v_mov_b32_e32 v76, 0
	v_mov_b32_e32 v77, 0
	v_mov_b32_e32 v78, 0
	v_mov_b32_e32 v79, 0
	v_mov_b32_e32 v80, 0
	v_mov_b32_e32 v81, 0
	v_mov_b32_e32 v82, 0
	v_mov_b32_e32 v83, 0
	v_mov_b32_e32 v84, 0
	v_mov_b32_e32 v85, 0
	v_mov_b32_e32 v86, 0
	v_mov_b32_e32 v87, 0
	v_mov_b32_e32 v88, 0
	v_mov_b32_e32 v89, 0
	v_mov_b32_e32 v90, 0
	v_mov_b32_e32 v91, 0
	s_mov_b32 s31, 0
	s_mov_b32 s34, 0
	s_mov_b32 s35, s53
	s_mov_b32 s38, s53
	s_mov_b32 s39, 0
	s_mov_b32 s40, 0
	s_mov_b32 s41, s42
	s_and_b32 s4, s38, 31
	s_mul_i32 s4, s4, 0x60000
	s_add_u32 s44, s48, s4
	s_addc_u32 s45, s49, 0
	s_lshr_b32 s4, s38, 5
	s_mul_i32 s4, s4, 0x40000
	s_add_u32 s46, s50, s4
	s_addc_u32 s47, s51, 0
	s_add_u32 m0, s41, 0x0
	s_nop 0
	global_load_lds_dwordx4 v148, s[44:45]
	s_add_u32 m0, s41, 0x2000
	s_nop 0
	global_load_lds_dwordx4 v149, s[44:45]
	s_add_u32 m0, s41, 0x4000
	s_nop 0
	global_load_lds_dwordx4 v150, s[44:45]
	s_add_u32 m0, s41, 0x6000
	s_nop 0
	global_load_lds_dwordx4 v148, s[46:47]
	s_add_u32 m0, s41, 0x8000
	s_nop 0
	global_load_lds_dwordx4 v149, s[46:47]
	s_add_u32 s39, s39, 1
	s_add_u32 s44, s44, 0x80
	s_addc_u32 s45, s45, 0
	s_add_u32 s46, s46, 0x80
	s_addc_u32 s47, s47, 0
	s_cmp_lt_u32 s39, 16
	s_cbranch_scc1 .Lgm_wo_dadv1
	s_mov_b32 s39, 0
	s_add_u32 s4, s38, s52
	s_cmp_lt_u32 s4, s54
	s_cselect_b32 s38, s4, s38
	s_and_b32 s4, s38, 31
	s_mul_i32 s4, s4, 0x60000
	s_add_u32 s44, s48, s4
	s_addc_u32 s45, s49, 0
	s_lshr_b32 s4, s38, 5
	s_mul_i32 s4, s4, 0x40000
	s_add_u32 s46, s50, s4
	s_addc_u32 s47, s51, 0

.Lgm_wo_dadv3:
	ds_read_b128 v[120:123], v152 offset:0
	ds_read_b128 v[124:127], v152 offset:2048
	ds_read_b128 v[128:131], v152 offset:4096
	ds_read_b128 v[132:135], v154 offset:0
	ds_read_b128 v[136:139], v154 offset:2048
	ds_read_b128 v[140:143], v154 offset:4096
	ds_read_b128 v[144:147], v154 offset:6144
	s_waitcnt lgkmcnt(10)
	v_mfma_f32_16x16x32_bf16 v[44:47], v[92:95], v[104:107], v[44:47]
	v_mfma_f32_16x16x32_bf16 v[60:63], v[96:99], v[104:107], v[60:63]
	v_mfma_f32_16x16x32_bf16 v[76:79], v[100:103], v[104:107], v[76:79]
	s_waitcnt lgkmcnt(9)
	v_mfma_f32_16x16x32_bf16 v[48:51], v[92:95], v[108:111], v[48:51]
	v_mfma_f32_16x16x32_bf16 v[64:67], v[96:99], v[108:111], v[64:67]
	v_mfma_f32_16x16x32_bf16 v[80:83], v[100:103], v[108:111], v[80:83]
	s_waitcnt lgkmcnt(8)
	v_mfma_f32_16x16x32_bf16 v[52:55], v[92:95], v[112:115], v[52:55]
	v_mfma_f32_16x16x32_bf16 v[68:71], v[96:99], v[112:115], v[68:71]
	v_mfma_f32_16x16x32_bf16 v[84:87], v[100:103], v[112:115], v[84:87]
	s_waitcnt lgkmcnt(7)
	v_mfma_f32_16x16x32_bf16 v[56:59], v[92:95], v[116:119], v[56:59]
	v_mfma_f32_16x16x32_bf16 v[72:75], v[96:99], v[116:119], v[72:75]
	v_mfma_f32_16x16x32_bf16 v[88:91], v[100:103], v[116:119], v[88:91]
	s_waitcnt lgkmcnt(0)
	s_add_u32 s34, s34, 1
	s_cmp_lt_u32 s34, 16
	s_cbranch_scc1 .Lgm_wo_next_a
	v_mfma_f32_16x16x32_bf16 v[44:47], v[120:123], v[132:135], v[44:47]
	v_mfma_f32_16x16x32_bf16 v[60:63], v[124:127], v[132:135], v[60:63]
	v_mfma_f32_16x16x32_bf16 v[76:79], v[128:131], v[132:135], v[76:79]
	v_mfma_f32_16x16x32_bf16 v[48:51], v[120:123], v[136:139], v[48:51]
	v_mfma_f32_16x16x32_bf16 v[64:67], v[124:127], v[136:139], v[64:67]
	v_mfma_f32_16x16x32_bf16 v[80:83], v[128:131], v[136:139], v[80:83]
	v_mfma_f32_16x16x32_bf16 v[52:55], v[120:123], v[140:143], v[52:55]
	v_mfma_f32_16x16x32_bf16 v[68:71], v[124:127], v[140:143], v[68:71]
	v_mfma_f32_16x16x32_bf16 v[84:87], v[128:131], v[140:143], v[84:87]
	v_mfma_f32_16x16x32_bf16 v[56:59], v[120:123], v[144:147], v[56:59]
	v_mfma_f32_16x16x32_bf16 v[72:75], v[124:127], v[144:147], v[72:75]
	v_mfma_f32_16x16x32_bf16 v[88:91], v[128:131], v[144:147], v[88:91]
	s_and_b32 s6, s35, 31
	s_mul_i32 s6, s6, 192
	s_lshr_b32 s7, s35, 5
	s_lshl_b32 s7, s7, 7
	s_nop 7
	s_mul_i32 s4, s6, 0x1000
	s_lshl_b32 s5, s7, 2
	s_add_u32 s4, s4, s5
	v_add_u32_e32 v158, s4, v157
	v_add_u32_e32 v161, s6, v159
	v_lshl_add_u32 v162, s7, 2, v160
	s_sub_i32 s4, s6, 0xc00
	s_max_i32 s4, s4, 0
	s_lshr_b32 s4, s4, 10
	s_add_i32 s5, s6, -2881
	s_max_i32 s5, s5, 0
	s_lshr_b32 s5, s5, 10
	s_movk_i32 s7, 0x1400
	s_cmp_eq_u32 s4, 0
	s_cselect_b32 s7, 0x1000, s7
	s_mul_i32 s4, s4, 0x6000
	s_mul_i32 s5, s5, 0x6000
	v_mov_b32_e32 v163, v158
	v_add_u32_e32 v164, 0, v161
	v_cmp_gt_u32_e32 vcc, 0x1000, v164
	v_mov_b32_e32 v0, s98
	v_mov_b32_e32 v1, s99
	v_mov_b32_e32 v3, s58
	v_cndmask_b32_e32 v0, v0, v3, vcc
	v_mov_b32_e32 v3, s59
	v_cndmask_b32_e32 v1, v1, v3, vcc
	v_add_co_u32_e32 v0, vcc, v0, v163
	s_nop 1
	v_addc_co_u32_e32 v1, vcc, 0, v1, vcc
	global_load_dwordx4 v[92:95], v[0:1], off
	v_add_u32_e32 v163, 0x4000, v163
	v_add_u32_e32 v164, 4, v161
	v_cmp_gt_u32_e32 vcc, 0x1000, v164
	v_mov_b32_e32 v0, s98
	v_mov_b32_e32 v1, s99
	v_mov_b32_e32 v3, s58
	v_cndmask_b32_e32 v0, v0, v3, vcc
	v_mov_b32_e32 v3, s59
	v_cndmask_b32_e32 v1, v1, v3, vcc
	v_add_co_u32_e32 v0, vcc, v0, v163
	s_nop 1
	v_addc_co_u32_e32 v1, vcc, 0, v1, vcc
	global_load_dwordx4 v[96:99], v[0:1], off
	v_add_u32_e32 v163, 0x4000, v163
	v_add_u32_e32 v164, 8, v161
	v_cmp_gt_u32_e32 vcc, 0x1000, v164
	v_mov_b32_e32 v0, s98
	v_mov_b32_e32 v1, s99
	v_mov_b32_e32 v3, s58
	v_cndmask_b32_e32 v0, v0, v3, vcc
	v_mov_b32_e32 v3, s59
	v_cndmask_b32_e32 v1, v1, v3, vcc
	v_add_co_u32_e32 v0, vcc, v0, v163
	s_nop 1
	v_addc_co_u32_e32 v1, vcc, 0, v1, vcc
	global_load_dwordx4 v[100:103], v[0:1], off
	v_add_u32_e32 v163, 0x4000, v163
	v_add_u32_e32 v164, 12, v161
	v_cmp_gt_u32_e32 vcc, 0x1000, v164
	v_mov_b32_e32 v0, s98
	v_mov_b32_e32 v1, s99
	v_mov_b32_e32 v3, s58
	v_cndmask_b32_e32 v0, v0, v3, vcc
	v_mov_b32_e32 v3, s59
	v_cndmask_b32_e32 v1, v1, v3, vcc
	v_add_co_u32_e32 v0, vcc, v0, v163
	s_nop 1
	v_addc_co_u32_e32 v1, vcc, 0, v1, vcc
	global_load_dwordx4 v[104:107], v[0:1], off
	v_add_u32_e32 v163, 0x4000, v163
	v_add_u32_e32 v164, 16, v161
	v_cmp_gt_u32_e32 vcc, 0x1000, v164
	v_mov_b32_e32 v0, s98
	v_mov_b32_e32 v1, s99
	v_mov_b32_e32 v3, s58
	v_cndmask_b32_e32 v0, v0, v3, vcc
	v_mov_b32_e32 v3, s59
	v_cndmask_b32_e32 v1, v1, v3, vcc
	v_add_co_u32_e32 v0, vcc, v0, v163
	s_nop 1
	v_addc_co_u32_e32 v1, vcc, 0, v1, vcc
	global_load_dwordx4 v[108:111], v[0:1], off
	v_add_u32_e32 v163, 0x4000, v163
	v_add_u32_e32 v164, 20, v161
	v_cmp_gt_u32_e32 vcc, 0x1000, v164
	v_mov_b32_e32 v0, s98
	v_mov_b32_e32 v1, s99
	v_mov_b32_e32 v3, s58
	v_cndmask_b32_e32 v0, v0, v3, vcc
	v_mov_b32_e32 v3, s59
	v_cndmask_b32_e32 v1, v1, v3, vcc
	v_add_co_u32_e32 v0, vcc, v0, v163
	s_nop 1
	v_addc_co_u32_e32 v1, vcc, 0, v1, vcc
	global_load_dwordx4 v[112:115], v[0:1], off
	v_add_u32_e32 v163, 0x4000, v163
	v_add_u32_e32 v164, 24, v161
	v_cmp_gt_u32_e32 vcc, 0x1000, v164
	v_mov_b32_e32 v0, s98
	v_mov_b32_e32 v1, s99
	v_mov_b32_e32 v3, s58
	v_cndmask_b32_e32 v0, v0, v3, vcc
	v_mov_b32_e32 v3, s59
	v_cndmask_b32_e32 v1, v1, v3, vcc
	v_add_co_u32_e32 v0, vcc, v0, v163
	s_nop 1
	v_addc_co_u32_e32 v1, vcc, 0, v1, vcc
	global_load_dwordx4 v[116:119], v[0:1], off
	v_add_u32_e32 v163, 0x4000, v163
	v_add_u32_e32 v164, 28, v161
	v_cmp_gt_u32_e32 vcc, 0x1000, v164
	v_mov_b32_e32 v0, s98
	v_mov_b32_e32 v1, s99
	v_mov_b32_e32 v3, s58
	v_cndmask_b32_e32 v0, v0, v3, vcc
	v_mov_b32_e32 v3, s59
	v_cndmask_b32_e32 v1, v1, v3, vcc
	v_add_co_u32_e32 v0, vcc, v0, v163
	s_nop 1
	v_addc_co_u32_e32 v1, vcc, 0, v1, vcc
	global_load_dwordx4 v[120:123], v[0:1], off
	v_add_u32_e32 v163, 0x4000, v163
	v_add_u32_e32 v164, 32, v161
	v_cmp_gt_u32_e32 vcc, 0x1000, v164
	v_mov_b32_e32 v0, s98
	v_mov_b32_e32 v1, s99
	v_mov_b32_e32 v3, s58
	v_cndmask_b32_e32 v0, v0, v3, vcc
	v_mov_b32_e32 v3, s59
	v_cndmask_b32_e32 v1, v1, v3, vcc
	v_add_co_u32_e32 v0, vcc, v0, v163
	s_nop 1
	v_addc_co_u32_e32 v1, vcc, 0, v1, vcc
	global_load_dwordx4 v[124:127], v[0:1], off
	v_add_u32_e32 v163, 0x4000, v163
	v_add_u32_e32 v164, 36, v161
	v_cmp_gt_u32_e32 vcc, 0x1000, v164
	v_mov_b32_e32 v0, s98
	v_mov_b32_e32 v1, s99
	v_mov_b32_e32 v3, s58
	v_cndmask_b32_e32 v0, v0, v3, vcc
	v_mov_b32_e32 v3, s59
	v_cndmask_b32_e32 v1, v1, v3, vcc
	v_add_co_u32_e32 v0, vcc, v0, v163
	s_nop 1
	v_addc_co_u32_e32 v1, vcc, 0, v1, vcc
	global_load_dwordx4 v[128:131], v[0:1], off
	v_add_u32_e32 v163, 0x4000, v163
	v_add_u32_e32 v164, 40, v161
	v_cmp_gt_u32_e32 vcc, 0x1000, v164
	v_mov_b32_e32 v0, s98
	v_mov_b32_e32 v1, s99
	v_mov_b32_e32 v3, s58
	v_cndmask_b32_e32 v0, v0, v3, vcc
	v_mov_b32_e32 v3, s59
	v_cndmask_b32_e32 v1, v1, v3, vcc
	v_add_co_u32_e32 v0, vcc, v0, v163
	s_nop 1
	v_addc_co_u32_e32 v1, vcc, 0, v1, vcc
	global_load_dwordx4 v[132:135], v[0:1], off
	v_add_u32_e32 v163, 0x4000, v163
	v_add_u32_e32 v164, 44, v161
	v_cmp_gt_u32_e32 vcc, 0x1000, v164
	v_mov_b32_e32 v0, s98
	v_mov_b32_e32 v1, s99
	v_mov_b32_e32 v3, s58
	v_cndmask_b32_e32 v0, v0, v3, vcc
	v_mov_b32_e32 v3, s59
	v_cndmask_b32_e32 v1, v1, v3, vcc
	v_add_co_u32_e32 v0, vcc, v0, v163
	s_nop 1
	v_addc_co_u32_e32 v1, vcc, 0, v1, vcc
	global_load_dwordx4 v[136:139], v[0:1], off
	v_add_u32_e32 v163, 0x4000, v163
	v_add_u32_e32 v164, s4, v162
	global_load_dwordx4 v[4:7], v164, s[100:101]
	v_add_u32_e32 v164, s5, v162
	global_load_dwordx4 v[8:11], v164, s[100:101]
	ds_write_b32 v155, v44 offset:0
	ds_write_b32 v155, v45 offset:272
	ds_write_b32 v155, v46 offset:544
	ds_write_b32 v155, v47 offset:816
	ds_write_b32 v155, v48 offset:64
	ds_write_b32 v155, v49 offset:336
	ds_write_b32 v155, v50 offset:608
	ds_write_b32 v155, v51 offset:880
	ds_write_b32 v155, v52 offset:128
	ds_write_b32 v155, v53 offset:400
	ds_write_b32 v155, v54 offset:672
	ds_write_b32 v155, v55 offset:944
	ds_write_b32 v155, v56 offset:192
	ds_write_b32 v155, v57 offset:464
	ds_write_b32 v155, v58 offset:736
	ds_write_b32 v155, v59 offset:1008
	s_waitcnt lgkmcnt(0)
	ds_read_b128 v[16:19], v156 offset:0
	ds_read_b128 v[20:23], v156 offset:1088
	ds_read_b128 v[24:27], v156 offset:2176
	ds_read_b128 v[28:31], v156 offset:3264
	v_add_u32_e32 v164, 0, v161
	v_cmp_le_u32_e32 vcc, s7, v164
	s_waitcnt vmcnt(0)
	s_waitcnt lgkmcnt(3)
	v_cndmask_b32_e32 v12, v4, v8, vcc
	v_cndmask_b32_e32 v13, v5, v9, vcc
	v_cndmask_b32_e32 v14, v6, v10, vcc
	v_cndmask_b32_e32 v15, v7, v11, vcc
	v_fmac_f32_e32 v92, v12, v16
	v_fmac_f32_e32 v93, v13, v17
	v_fmac_f32_e32 v94, v14, v18
	v_fmac_f32_e32 v95, v15, v19
	global_store_dwordx4 v158, v[92:95], s[56:57] sc0 sc1
	v_add_u32_e32 v158, 0x4000, v158
	v_add_u32_e32 v164, 4, v161
	v_cmp_le_u32_e32 vcc, s7, v164
	s_waitcnt vmcnt(1)
	s_waitcnt lgkmcnt(2)
	v_cndmask_b32_e32 v12, v4, v8, vcc
	v_cndmask_b32_e32 v13, v5, v9, vcc
	v_cndmask_b32_e32 v14, v6, v10, vcc
	v_cndmask_b32_e32 v15, v7, v11, vcc
	v_fmac_f32_e32 v96, v12, v20
	v_fmac_f32_e32 v97, v13, v21
	v_fmac_f32_e32 v98, v14, v22
	v_fmac_f32_e32 v99, v15, v23
	global_store_dwordx4 v158, v[96:99], s[56:57] sc0 sc1
	v_add_u32_e32 v158, 0x4000, v158
	v_add_u32_e32 v164, 8, v161
	v_cmp_le_u32_e32 vcc, s7, v164
	s_waitcnt vmcnt(2)
	s_waitcnt lgkmcnt(1)
	v_cndmask_b32_e32 v12, v4, v8, vcc
	v_cndmask_b32_e32 v13, v5, v9, vcc
	v_cndmask_b32_e32 v14, v6, v10, vcc
	v_cndmask_b32_e32 v15, v7, v11, vcc
	v_fmac_f32_e32 v100, v12, v24
	v_fmac_f32_e32 v101, v13, v25
	v_fmac_f32_e32 v102, v14, v26
	v_fmac_f32_e32 v103, v15, v27
	global_store_dwordx4 v158, v[100:103], s[56:57] sc0 sc1
	v_add_u32_e32 v158, 0x4000, v158
	v_add_u32_e32 v164, 12, v161
	v_cmp_le_u32_e32 vcc, s7, v164
	s_waitcnt vmcnt(3)
	s_waitcnt lgkmcnt(0)
	v_cndmask_b32_e32 v12, v4, v8, vcc
	v_cndmask_b32_e32 v13, v5, v9, vcc
	v_cndmask_b32_e32 v14, v6, v10, vcc
	v_cndmask_b32_e32 v15, v7, v11, vcc
	v_fmac_f32_e32 v104, v12, v28
	v_fmac_f32_e32 v105, v13, v29
	v_fmac_f32_e32 v106, v14, v30
	v_fmac_f32_e32 v107, v15, v31
	global_store_dwordx4 v158, v[104:107], s[56:57] sc0 sc1
	v_add_u32_e32 v158, 0x4000, v158
	ds_write_b32 v155, v60 offset:0
	ds_write_b32 v155, v61 offset:272
	ds_write_b32 v155, v62 offset:544
	ds_write_b32 v155, v63 offset:816
	ds_write_b32 v155, v64 offset:64
	ds_write_b32 v155, v65 offset:336
	ds_write_b32 v155, v66 offset:608
	ds_write_b32 v155, v67 offset:880
	ds_write_b32 v155, v68 offset:128
	ds_write_b32 v155, v69 offset:400
	ds_write_b32 v155, v70 offset:672
	ds_write_b32 v155, v71 offset:944
	ds_write_b32 v155, v72 offset:192
	ds_write_b32 v155, v73 offset:464
	ds_write_b32 v155, v74 offset:736
	ds_write_b32 v155, v75 offset:1008
	s_waitcnt lgkmcnt(0)
	ds_read_b128 v[16:19], v156 offset:0
	ds_read_b128 v[20:23], v156 offset:1088
	ds_read_b128 v[24:27], v156 offset:2176
	ds_read_b128 v[28:31], v156 offset:3264
	v_add_u32_e32 v164, 16, v161
	v_cmp_le_u32_e32 vcc, s7, v164
	s_waitcnt vmcnt(4)
	s_waitcnt lgkmcnt(3)
	v_cndmask_b32_e32 v12, v4, v8, vcc
	v_cndmask_b32_e32 v13, v5, v9, vcc
	v_cndmask_b32_e32 v14, v6, v10, vcc
	v_cndmask_b32_e32 v15, v7, v11, vcc
	v_fmac_f32_e32 v108, v12, v16
	v_fmac_f32_e32 v109, v13, v17
	v_fmac_f32_e32 v110, v14, v18
	v_fmac_f32_e32 v111, v15, v19
	global_store_dwordx4 v158, v[108:111], s[56:57] sc0 sc1
	v_add_u32_e32 v158, 0x4000, v158
	v_add_u32_e32 v164, 20, v161
	v_cmp_le_u32_e32 vcc, s7, v164
	s_waitcnt vmcnt(5)
	s_waitcnt lgkmcnt(2)
	v_cndmask_b32_e32 v12, v4, v8, vcc
	v_cndmask_b32_e32 v13, v5, v9, vcc
	v_cndmask_b32_e32 v14, v6, v10, vcc
	v_cndmask_b32_e32 v15, v7, v11, vcc
	v_fmac_f32_e32 v112, v12, v20
	v_fmac_f32_e32 v113, v13, v21
	v_fmac_f32_e32 v114, v14, v22
	v_fmac_f32_e32 v115, v15, v23
	global_store_dwordx4 v158, v[112:115], s[56:57] sc0 sc1
	v_add_u32_e32 v158, 0x4000, v158
	v_add_u32_e32 v164, 24, v161
	v_cmp_le_u32_e32 vcc, s7, v164
	s_waitcnt vmcnt(6)
	s_waitcnt lgkmcnt(1)
	v_cndmask_b32_e32 v12, v4, v8, vcc
	v_cndmask_b32_e32 v13, v5, v9, vcc
	v_cndmask_b32_e32 v14, v6, v10, vcc
	v_cndmask_b32_e32 v15, v7, v11, vcc
	v_fmac_f32_e32 v116, v12, v24
	v_fmac_f32_e32 v117, v13, v25
	v_fmac_f32_e32 v118, v14, v26
	v_fmac_f32_e32 v119, v15, v27
	global_store_dwordx4 v158, v[116:119], s[56:57] sc0 sc1
	v_add_u32_e32 v158, 0x4000, v158
	v_add_u32_e32 v164, 28, v161
	v_cmp_le_u32_e32 vcc, s7, v164
	s_waitcnt vmcnt(7)
	s_waitcnt lgkmcnt(0)
	v_cndmask_b32_e32 v12, v4, v8, vcc
	v_cndmask_b32_e32 v13, v5, v9, vcc
	v_cndmask_b32_e32 v14, v6, v10, vcc
	v_cndmask_b32_e32 v15, v7, v11, vcc
	v_fmac_f32_e32 v120, v12, v28
	v_fmac_f32_e32 v121, v13, v29
	v_fmac_f32_e32 v122, v14, v30
	v_fmac_f32_e32 v123, v15, v31
	global_store_dwordx4 v158, v[120:123], s[56:57] sc0 sc1
	v_add_u32_e32 v158, 0x4000, v158
	ds_write_b32 v155, v76 offset:0
	ds_write_b32 v155, v77 offset:272
	ds_write_b32 v155, v78 offset:544
	ds_write_b32 v155, v79 offset:816
	ds_write_b32 v155, v80 offset:64
	ds_write_b32 v155, v81 offset:336
	ds_write_b32 v155, v82 offset:608
	ds_write_b32 v155, v83 offset:880
	ds_write_b32 v155, v84 offset:128
	ds_write_b32 v155, v85 offset:400
	ds_write_b32 v155, v86 offset:672
	ds_write_b32 v155, v87 offset:944
	ds_write_b32 v155, v88 offset:192
	ds_write_b32 v155, v89 offset:464
	ds_write_b32 v155, v90 offset:736
	ds_write_b32 v155, v91 offset:1008
	s_waitcnt lgkmcnt(0)
	ds_read_b128 v[16:19], v156 offset:0
	ds_read_b128 v[20:23], v156 offset:1088
	ds_read_b128 v[24:27], v156 offset:2176
	ds_read_b128 v[28:31], v156 offset:3264
	v_add_u32_e32 v164, 32, v161
	v_cmp_le_u32_e32 vcc, s7, v164
	s_waitcnt vmcnt(8)
	s_waitcnt lgkmcnt(3)
	v_cndmask_b32_e32 v12, v4, v8, vcc
	v_cndmask_b32_e32 v13, v5, v9, vcc
	v_cndmask_b32_e32 v14, v6, v10, vcc
	v_cndmask_b32_e32 v15, v7, v11, vcc
	v_fmac_f32_e32 v124, v12, v16
	v_fmac_f32_e32 v125, v13, v17
	v_fmac_f32_e32 v126, v14, v18
	v_fmac_f32_e32 v127, v15, v19
	global_store_dwordx4 v158, v[124:127], s[56:57] sc0 sc1
	v_add_u32_e32 v158, 0x4000, v158
	v_add_u32_e32 v164, 36, v161
	v_cmp_le_u32_e32 vcc, s7, v164
	s_waitcnt vmcnt(9)
	s_waitcnt lgkmcnt(2)
	v_cndmask_b32_e32 v12, v4, v8, vcc
	v_cndmask_b32_e32 v13, v5, v9, vcc
	v_cndmask_b32_e32 v14, v6, v10, vcc
	v_cndmask_b32_e32 v15, v7, v11, vcc
	v_fmac_f32_e32 v128, v12, v20
	v_fmac_f32_e32 v129, v13, v21
	v_fmac_f32_e32 v130, v14, v22
	v_fmac_f32_e32 v131, v15, v23
	global_store_dwordx4 v158, v[128:131], s[56:57] sc0 sc1
	v_add_u32_e32 v158, 0x4000, v158
	v_add_u32_e32 v164, 40, v161
	v_cmp_le_u32_e32 vcc, s7, v164
	s_waitcnt vmcnt(10)
	s_waitcnt lgkmcnt(1)
	v_cndmask_b32_e32 v12, v4, v8, vcc
	v_cndmask_b32_e32 v13, v5, v9, vcc
	v_cndmask_b32_e32 v14, v6, v10, vcc
	v_cndmask_b32_e32 v15, v7, v11, vcc
	v_fmac_f32_e32 v132, v12, v24
	v_fmac_f32_e32 v133, v13, v25
	v_fmac_f32_e32 v134, v14, v26
	v_fmac_f32_e32 v135, v15, v27
	global_store_dwordx4 v158, v[132:135], s[56:57] sc0 sc1
	v_add_u32_e32 v158, 0x4000, v158
	v_add_u32_e32 v164, 44, v161
	v_cmp_le_u32_e32 vcc, s7, v164
	s_waitcnt vmcnt(11)
	s_waitcnt lgkmcnt(0)
	v_cndmask_b32_e32 v12, v4, v8, vcc
	v_cndmask_b32_e32 v13, v5, v9, vcc
	v_cndmask_b32_e32 v14, v6, v10, vcc
	v_cndmask_b32_e32 v15, v7, v11, vcc
	v_fmac_f32_e32 v136, v12, v28
	v_fmac_f32_e32 v137, v13, v29
	v_fmac_f32_e32 v138, v14, v30
	v_fmac_f32_e32 v139, v15, v31
	global_store_dwordx4 v158, v[136:139], s[56:57] sc0 sc1
	v_add_u32_e32 v158, 0x4000, v158
	v_mov_b32_e32 v44, 0
	v_mov_b32_e32 v45, 0
	v_mov_b32_e32 v46, 0
	v_mov_b32_e32 v47, 0
	v_mov_b32_e32 v48, 0
	v_mov_b32_e32 v49, 0
	v_mov_b32_e32 v50, 0
	v_mov_b32_e32 v51, 0
	v_mov_b32_e32 v52, 0
	v_mov_b32_e32 v53, 0
	v_mov_b32_e32 v54, 0
	v_mov_b32_e32 v55, 0
	v_mov_b32_e32 v56, 0
	v_mov_b32_e32 v57, 0
	v_mov_b32_e32 v58, 0
	v_mov_b32_e32 v59, 0
	v_mov_b32_e32 v60, 0
	v_mov_b32_e32 v61, 0
	v_mov_b32_e32 v62, 0
	v_mov_b32_e32 v63, 0
	v_mov_b32_e32 v64, 0
	v_mov_b32_e32 v65, 0
	v_mov_b32_e32 v66, 0
	v_mov_b32_e32 v67, 0
	v_mov_b32_e32 v68, 0
	v_mov_b32_e32 v69, 0
	v_mov_b32_e32 v70, 0
	v_mov_b32_e32 v71, 0
	v_mov_b32_e32 v72, 0
	v_mov_b32_e32 v73, 0
	v_mov_b32_e32 v74, 0
	v_mov_b32_e32 v75, 0
	v_mov_b32_e32 v76, 0
	v_mov_b32_e32 v77, 0
	v_mov_b32_e32 v78, 0
	v_mov_b32_e32 v79, 0
	v_mov_b32_e32 v80, 0
	v_mov_b32_e32 v81, 0
	v_mov_b32_e32 v82, 0
	v_mov_b32_e32 v83, 0
	v_mov_b32_e32 v84, 0
	v_mov_b32_e32 v85, 0
	v_mov_b32_e32 v86, 0
	v_mov_b32_e32 v87, 0
	v_mov_b32_e32 v88, 0
	v_mov_b32_e32 v89, 0
	v_mov_b32_e32 v90, 0
	v_mov_b32_e32 v91, 0
	s_mov_b32 s34, 0
	s_add_u32 s35, s35, s52
	s_add_u32 s31, s31, 1
	s_cmp_ge_u32 s31, s30
	s_cbranch_scc1 .Lgm_wo_exit
	s_waitcnt vmcnt(17)
	s_branch .Lgm_wo_rot_a

.Lgm_wi_cnt:
	s_add_u32 s30, s30, 16
	s_add_u32 s4, s4, s52
	s_cmp_lt_u32 s4, s54
	s_cbranch_scc1 .Lgm_wi_cnt
	s_add_u32 s48, s96, 0x2e24000
	s_addc_u32 s49, s97, 0
	s_mul_i32 s4, s36, 0x4c0000
	s_add_u32 s50, s96, 0x0
	s_addc_u32 s51, s97, 0
	s_add_u32 s50, s50, s4
	s_addc_u32 s51, s51, 0
	v_and_b32_e32 v0, 63, v206
	v_lshrrev_b32_e32 v1, 6, v206
	v_lshrrev_b32_e32 v3, 3, v0
	v_and_b32_e32 v4, 7, v0
	v_readfirstlane_b32 s42, v1
	v_xor_b32_e32 v4, v4, v3
	v_lshl_add_u32 v3, v1, 3, v3
	v_lshlrev_b32_e32 v3, 11, v3
	v_lshl_add_u32 v148, v4, 4, v3
	v_add_u32_e32 v149, 0x20000, v148
	v_add_u32_e32 v150, 0x40000, v148
	v_and_b32_e32 v5, 15, v0
	v_lshrrev_b32_e32 v6, 4, v0
	v_and_b32_e32 v7, 7, v5
	v_xor_b32_e32 v7, v7, v6
	v_lshlrev_b32_e32 v7, 4, v7
	v_lshrrev_b32_e32 v8, 1, v1
	v_and_b32_e32 v9, 1, v1
	v_mul_u32_u24_e32 v10, 48, v8
	v_add_u32_e32 v11, v10, v5
	v_lshl_add_u32 v151, v11, 7, v7
	v_xor_b32_e32 v152, 64, v151
	v_lshl_add_u32 v11, v9, 6, v5
	v_lshl_add_u32 v153, v11, 7, v7
	v_add_u32_e32 v153, 0x6000, v153
	v_xor_b32_e32 v154, 64, v153
	s_mul_i32 s5, s42, 4352
	s_mov_b32 s6, 0x1ec10
	s_cmp_lt_u32 s42, 4
	s_cselect_b32 s6, 0x1e000, s6
	s_add_u32 s5, s5, s6
	s_mov_b32 s43, s5
	v_mul_u32_u24_e32 v11, 1088, v6
	v_lshl_add_u32 v11, v5, 2, v11
	v_add_u32_e32 v155, s5, v11
	v_mul_u32_u24_e32 v11, 272, v6
	v_lshl_add_u32 v11, v5, 4, v11
	v_add_u32_e32 v156, s5, v11
	v_add_u32_e32 v11, v10, v6
	v_lshlrev_b32_e32 v12, 6, v9
	v_lshl_add_u32 v12, v5, 2, v12
	s_mov_b32 s4, 0x2440
	v_mul_lo_u32 v13, v11, s4
	v_lshl_add_u32 v157, v12, 2, v13
	v_mov_b32_e32 v159, v12
	s_lshl_b32 s42, s42, 10
	v_mov_b32_e32 v44, 0
	v_mov_b32_e32 v45, 0
	v_mov_b32_e32 v46, 0
	v_mov_b32_e32 v47, 0
	v_mov_b32_e32 v48, 0
	v_mov_b32_e32 v49, 0
	v_mov_b32_e32 v50, 0
	v_mov_b32_e32 v51, 0
	v_mov_b32_e32 v52, 0
	v_mov_b32_e32 v53, 0
	v_mov_b32_e32 v54, 0
	v_mov_b32_e32 v55, 0
	v_mov_b32_e32 v56, 0
	v_mov_b32_e32 v57, 0
	v_mov_b32_e32 v58, 0
	v_mov_b32_e32 v59, 0
	v_mov_b32_e32 v60, 0
	v_mov_b32_e32 v61, 0
	v_mov_b32_e32 v62, 0
	v_mov_b32_e32 v63, 0
	v_mov_b32_e32 v64, 0
	v_mov_b32_e32 v65, 0
	v_mov_b32_e32 v66, 0
	v_mov_b32_e32 v67, 0
	v_mov_b32_e32 v68, 0
	v_mov_b32_e32 v69, 0
	v_mov_b32_e32 v70, 0
	v_mov_b32_e32 v71, 0
	v_mov_b32_e32 v72, 0
	v_mov_b32_e32 v73, 0
	v_mov_b32_e32 v74, 0
	v_mov_b32_e32 v75, 0
	v_mov_b32_e32 v76, 0
	v_mov_b32_e32 v77, 0
	v_mov_b32_e32 v78, 0
	v_mov_b32_e32 v79, 0
	v_mov_b32_e32 v80, 0
	v_mov_b32_e32 v81, 0
	v_mov_b32_e32 v82, 0
	v_mov_b32_e32 v83, 0
	v_mov_b32_e32 v84, 0
	v_mov_b32_e32 v85, 0
	v_mov_b32_e32 v86, 0
	v_mov_b32_e32 v87, 0
	v_mov_b32_e32 v88, 0
	v_mov_b32_e32 v89, 0
	v_mov_b32_e32 v90, 0
	v_mov_b32_e32 v91, 0
	s_mov_b32 s31, 0
	s_mov_b32 s34, 0
	s_mov_b32 s35, s53
	s_mov_b32 s38, s53
	s_mov_b32 s39, 0
	s_mov_b32 s40, 0
	s_mov_b32 s41, s42
	s_and_b32 s4, s38, 31
	s_mul_i32 s4, s4, 0x60000
	s_add_u32 s44, s48, s4
	s_addc_u32 s45, s49, 0
	s_lshr_b32 s4, s38, 5
	s_mul_i32 s4, s4, 0x40000
	s_add_u32 s46, s50, s4
	s_addc_u32 s47, s51, 0
	s_add_u32 m0, s41, 0x0
	s_nop 0
	global_load_lds_dwordx4 v148, s[44:45]
	s_add_u32 m0, s41, 0x2000
	s_nop 0
	global_load_lds_dwordx4 v149, s[44:45]
	s_add_u32 m0, s41, 0x4000
	s_nop 0
	global_load_lds_dwordx4 v150, s[44:45]
	s_add_u32 m0, s41, 0x6000
	s_nop 0
	global_load_lds_dwordx4 v148, s[46:47]
	s_add_u32 m0, s41, 0x8000
	s_nop 0
	global_load_lds_dwordx4 v149, s[46:47]
	s_add_u32 s39, s39, 1
	s_add_u32 s44, s44, 0x80
	s_addc_u32 s45, s45, 0
	s_add_u32 s46, s46, 0x80
	s_addc_u32 s47, s47, 0
	s_cmp_lt_u32 s39, 16
	s_cbranch_scc1 .Lgm_wi_dadv1
	s_mov_b32 s39, 0
	s_add_u32 s4, s38, s52
	s_cmp_lt_u32 s4, s54
	s_cselect_b32 s38, s4, s38
	s_and_b32 s4, s38, 31
	s_mul_i32 s4, s4, 0x60000
	s_add_u32 s44, s48, s4
	s_addc_u32 s45, s49, 0
	s_lshr_b32 s4, s38, 5
	s_mul_i32 s4, s4, 0x40000
	s_add_u32 s46, s50, s4
	s_addc_u32 s47, s51, 0

.Lgm_wi_dadv3:
	ds_read_b128 v[120:123], v152 offset:0
	ds_read_b128 v[124:127], v152 offset:2048
	ds_read_b128 v[128:131], v152 offset:4096
	ds_read_b128 v[132:135], v154 offset:0
	ds_read_b128 v[136:139], v154 offset:2048
	ds_read_b128 v[140:143], v154 offset:4096
	ds_read_b128 v[144:147], v154 offset:6144
	s_waitcnt lgkmcnt(10)
	v_mfma_f32_16x16x32_bf16 v[44:47], v[92:95], v[104:107], v[44:47]
	v_mfma_f32_16x16x32_bf16 v[60:63], v[96:99], v[104:107], v[60:63]
	v_mfma_f32_16x16x32_bf16 v[76:79], v[100:103], v[104:107], v[76:79]
	s_waitcnt lgkmcnt(9)
	v_mfma_f32_16x16x32_bf16 v[48:51], v[92:95], v[108:111], v[48:51]
	v_mfma_f32_16x16x32_bf16 v[64:67], v[96:99], v[108:111], v[64:67]
	v_mfma_f32_16x16x32_bf16 v[80:83], v[100:103], v[108:111], v[80:83]
	s_waitcnt lgkmcnt(8)
	v_mfma_f32_16x16x32_bf16 v[52:55], v[92:95], v[112:115], v[52:55]
	v_mfma_f32_16x16x32_bf16 v[68:71], v[96:99], v[112:115], v[68:71]
	v_mfma_f32_16x16x32_bf16 v[84:87], v[100:103], v[112:115], v[84:87]
	s_waitcnt lgkmcnt(7)
	v_mfma_f32_16x16x32_bf16 v[56:59], v[92:95], v[116:119], v[56:59]
	v_mfma_f32_16x16x32_bf16 v[72:75], v[96:99], v[116:119], v[72:75]
	v_mfma_f32_16x16x32_bf16 v[88:91], v[100:103], v[116:119], v[88:91]
	s_waitcnt lgkmcnt(0)
	s_add_u32 s34, s34, 1
	s_cmp_lt_u32 s34, 16
	s_cbranch_scc1 .Lgm_wi_next_a
	v_mfma_f32_16x16x32_bf16 v[44:47], v[120:123], v[132:135], v[44:47]
	v_mfma_f32_16x16x32_bf16 v[60:63], v[124:127], v[132:135], v[60:63]
	v_mfma_f32_16x16x32_bf16 v[76:79], v[128:131], v[132:135], v[76:79]
	v_mfma_f32_16x16x32_bf16 v[48:51], v[120:123], v[136:139], v[48:51]
	v_mfma_f32_16x16x32_bf16 v[64:67], v[124:127], v[136:139], v[64:67]
	v_mfma_f32_16x16x32_bf16 v[80:83], v[128:131], v[136:139], v[80:83]
	v_mfma_f32_16x16x32_bf16 v[52:55], v[120:123], v[140:143], v[52:55]
	v_mfma_f32_16x16x32_bf16 v[68:71], v[124:127], v[140:143], v[68:71]
	v_mfma_f32_16x16x32_bf16 v[84:87], v[128:131], v[140:143], v[84:87]
	v_mfma_f32_16x16x32_bf16 v[56:59], v[120:123], v[144:147], v[56:59]
	v_mfma_f32_16x16x32_bf16 v[72:75], v[124:127], v[144:147], v[72:75]
	v_mfma_f32_16x16x32_bf16 v[88:91], v[128:131], v[144:147], v[88:91]
	s_and_b32 s6, s35, 31
	s_mul_i32 s6, s6, 192
	s_lshr_b32 s7, s35, 5
	s_lshl_b32 s7, s7, 7
	s_nop 7
	s_mul_i32 s4, s6, 0x2440
	s_lshl_b32 s5, s7, 2
	s_add_u32 s4, s4, s5
	v_add_u32_e32 v158, s4, v157
	v_add_u32_e32 v161, s7, v159
	s_mov_b32 s4, 0x910
	v_cmp_gt_u32_e32 vcc, s4, v161
	s_mov_b64 s[4:5], exec
	ds_write_b32 v155, v44 offset:0
	ds_write_b32 v155, v45 offset:272
	ds_write_b32 v155, v46 offset:544
	ds_write_b32 v155, v47 offset:816
	ds_write_b32 v155, v48 offset:64
	ds_write_b32 v155, v49 offset:336
	ds_write_b32 v155, v50 offset:608
	ds_write_b32 v155, v51 offset:880
	ds_write_b32 v155, v52 offset:128
	ds_write_b32 v155, v53 offset:400
	ds_write_b32 v155, v54 offset:672
	ds_write_b32 v155, v55 offset:944
	ds_write_b32 v155, v56 offset:192
	ds_write_b32 v155, v57 offset:464
	ds_write_b32 v155, v58 offset:736
	ds_write_b32 v155, v59 offset:1008
	s_waitcnt lgkmcnt(0)
	ds_read_b128 v[16:19], v156 offset:0
	ds_read_b128 v[20:23], v156 offset:1088
	ds_read_b128 v[24:27], v156 offset:2176
	ds_read_b128 v[28:31], v156 offset:3264
	s_waitcnt lgkmcnt(0)
	s_and_b64 exec, s[4:5], vcc
	global_store_dwordx4 v158, v[16:19], s[56:57] sc0 sc1
	v_add_u32_e32 v158, 0x9100, v158
	global_store_dwordx4 v158, v[20:23], s[56:57] sc0 sc1
	v_add_u32_e32 v158, 0x9100, v158
	global_store_dwordx4 v158, v[24:27], s[56:57] sc0 sc1
	v_add_u32_e32 v158, 0x9100, v158
	global_store_dwordx4 v158, v[28:31], s[56:57] sc0 sc1
	v_add_u32_e32 v158, 0x9100, v158
	s_mov_b64 exec, s[4:5]
	s_nop 1
	ds_write_b32 v155, v60 offset:0
	ds_write_b32 v155, v61 offset:272
	ds_write_b32 v155, v62 offset:544
	ds_write_b32 v155, v63 offset:816
	ds_write_b32 v155, v64 offset:64
	ds_write_b32 v155, v65 offset:336
	ds_write_b32 v155, v66 offset:608
	ds_write_b32 v155, v67 offset:880
	ds_write_b32 v155, v68 offset:128
	ds_write_b32 v155, v69 offset:400
	ds_write_b32 v155, v70 offset:672
	ds_write_b32 v155, v71 offset:944
	ds_write_b32 v155, v72 offset:192
	ds_write_b32 v155, v73 offset:464
	ds_write_b32 v155, v74 offset:736
	ds_write_b32 v155, v75 offset:1008
	s_waitcnt lgkmcnt(0)
	ds_read_b128 v[16:19], v156 offset:0
	ds_read_b128 v[20:23], v156 offset:1088
	ds_read_b128 v[24:27], v156 offset:2176
	ds_read_b128 v[28:31], v156 offset:3264
	s_waitcnt lgkmcnt(0)
	s_and_b64 exec, s[4:5], vcc
	global_store_dwordx4 v158, v[16:19], s[56:57] sc0 sc1
	v_add_u32_e32 v158, 0x9100, v158
	global_store_dwordx4 v158, v[20:23], s[56:57] sc0 sc1
	v_add_u32_e32 v158, 0x9100, v158
	global_store_dwordx4 v158, v[24:27], s[56:57] sc0 sc1
	v_add_u32_e32 v158, 0x9100, v158
	global_store_dwordx4 v158, v[28:31], s[56:57] sc0 sc1
	v_add_u32_e32 v158, 0x9100, v158
	s_mov_b64 exec, s[4:5]
	s_nop 1
	ds_write_b32 v155, v76 offset:0
	ds_write_b32 v155, v77 offset:272
	ds_write_b32 v155, v78 offset:544
	ds_write_b32 v155, v79 offset:816
	ds_write_b32 v155, v80 offset:64
	ds_write_b32 v155, v81 offset:336
	ds_write_b32 v155, v82 offset:608
	ds_write_b32 v155, v83 offset:880
	ds_write_b32 v155, v84 offset:128
	ds_write_b32 v155, v85 offset:400
	ds_write_b32 v155, v86 offset:672
	ds_write_b32 v155, v87 offset:944
	ds_write_b32 v155, v88 offset:192
	ds_write_b32 v155, v89 offset:464
	ds_write_b32 v155, v90 offset:736
	ds_write_b32 v155, v91 offset:1008
	s_waitcnt lgkmcnt(0)
	ds_read_b128 v[16:19], v156 offset:0
	ds_read_b128 v[20:23], v156 offset:1088
	ds_read_b128 v[24:27], v156 offset:2176
	ds_read_b128 v[28:31], v156 offset:3264
	s_waitcnt lgkmcnt(0)
	s_and_b64 exec, s[4:5], vcc
	global_store_dwordx4 v158, v[16:19], s[56:57] sc0 sc1
	v_add_u32_e32 v158, 0x9100, v158
	global_store_dwordx4 v158, v[20:23], s[56:57] sc0 sc1
	v_add_u32_e32 v158, 0x9100, v158
	global_store_dwordx4 v158, v[24:27], s[56:57] sc0 sc1
	v_add_u32_e32 v158, 0x9100, v158
	global_store_dwordx4 v158, v[28:31], s[56:57] sc0 sc1
	v_add_u32_e32 v158, 0x9100, v158
	s_mov_b64 exec, s[4:5]
	s_nop 1
	v_mov_b32_e32 v44, 0
	v_mov_b32_e32 v45, 0
	v_mov_b32_e32 v46, 0
	v_mov_b32_e32 v47, 0
	v_mov_b32_e32 v48, 0
	v_mov_b32_e32 v49, 0
	v_mov_b32_e32 v50, 0
	v_mov_b32_e32 v51, 0
	v_mov_b32_e32 v52, 0
	v_mov_b32_e32 v53, 0
	v_mov_b32_e32 v54, 0
	v_mov_b32_e32 v55, 0
	v_mov_b32_e32 v56, 0
	v_mov_b32_e32 v57, 0
	v_mov_b32_e32 v58, 0
	v_mov_b32_e32 v59, 0
	v_mov_b32_e32 v60, 0
	v_mov_b32_e32 v61, 0
	v_mov_b32_e32 v62, 0
	v_mov_b32_e32 v63, 0
	v_mov_b32_e32 v64, 0
	v_mov_b32_e32 v65, 0
	v_mov_b32_e32 v66, 0
	v_mov_b32_e32 v67, 0
	v_mov_b32_e32 v68, 0
	v_mov_b32_e32 v69, 0
	v_mov_b32_e32 v70, 0
	v_mov_b32_e32 v71, 0
	v_mov_b32_e32 v72, 0
	v_mov_b32_e32 v73, 0
	v_mov_b32_e32 v74, 0
	v_mov_b32_e32 v75, 0
	v_mov_b32_e32 v76, 0
	v_mov_b32_e32 v77, 0
	v_mov_b32_e32 v78, 0
	v_mov_b32_e32 v79, 0
	v_mov_b32_e32 v80, 0
	v_mov_b32_e32 v81, 0
	v_mov_b32_e32 v82, 0
	v_mov_b32_e32 v83, 0
	v_mov_b32_e32 v84, 0
	v_mov_b32_e32 v85, 0
	v_mov_b32_e32 v86, 0
	v_mov_b32_e32 v87, 0
	v_mov_b32_e32 v88, 0
	v_mov_b32_e32 v89, 0
	v_mov_b32_e32 v90, 0
	v_mov_b32_e32 v91, 0
	s_mov_b32 s34, 0
	s_add_u32 s35, s35, s52
	s_add_u32 s31, s31, 1
	s_cmp_ge_u32 s31, s30
	s_cbranch_scc1 .Lgm_wi_exit
	s_waitcnt vmcnt(17)
	s_branch .Lgm_wi_rot_a

.LBB0_572:
	s_cmpk_gt_i32 s35, 0x17f
	s_mov_b64 s[38:39], -1
	s_cbranch_scc0 .LBB0_619
	s_and_b32 s42, s35, 3
	s_cmpk_gt_u32 s35, 0x47f
	s_cbranch_scc0 .LBB0_575
	v_mov_b32_e32 v3, v206
	s_or_b32 s40, s42, s4
	v_ashrrev_i32_e32 v0, 2, v3
	s_add_i32 s38, s35, 0xfffffb80
	s_ashr_i32 s41, s40, 31
	v_and_b32_e32 v0, -16, v0
	s_lshr_b32 s92, s38, 2
	s_lshl_b64 s[38:39], s[40:41], 7
	v_ashrrev_i32_e32 v1, 31, v0
	s_waitcnt vmcnt(0)
	v_and_b32_e32 v40, 15, v3
	v_lshl_add_u64 v[4:5], s[38:39], 0, v[0:1]
	v_or_b32_e32 v4, v4, v40
	v_readlane_b32 s6, v236, 1
	s_lshl_b64 s[38:39], s[92:93], 8
	s_lshl_b32 s41, s42, 6
	v_lshlrev_b64 v[4:5], 8, v[4:5]
	v_readlane_b32 s7, v236, 2
	s_or_b32 s38, s38, s41
	v_or_b32_e32 v6, s38, v40
	v_lshl_add_u64 v[4:5], s[6:7], 0, v[4:5]
	v_mov_b32_e32 v7, s39
	v_readlane_b32 s6, v236, 41
	v_lshlrev_b64 v[6:7], 8, v[6:7]
	v_bfe_u32 v1, v3, 4, 2
	v_readlane_b32 s7, v236, 42
	v_lshlrev_b32_e32 v10, 4, v1
	v_mov_b32_e32 v11, v2
	v_lshl_add_u64 v[8:9], s[6:7], 0, v[6:7]
	v_lshl_add_u64 v[32:33], v[8:9], 0, v[10:11]
	s_movk_i32 s6, 0x1000
	v_add_co_u32_e32 v34, vcc, s6, v32
	v_lshl_add_u64 v[28:29], v[4:5], 0, v[10:11]
	s_nop 0
	v_addc_co_u32_e32 v35, vcc, 0, v33, vcc
	s_movk_i32 s6, 0x2000
	v_add_co_u32_e32 v36, vcc, s6, v32
	s_movk_i32 s6, 0x3000
	s_nop 1
	v_addc_co_u32_e32 v37, vcc, 0, v33, vcc
	v_add_co_u32_e32 v38, vcc, s6, v32
	s_nop 1
	v_addc_co_u32_e32 v39, vcc, 0, v33, vcc
	v_lshl_or_b32 v0, v1, 2, v0
	v_readlane_b32 s6, v236, 43
	s_lshl_b64 s[38:39], s[92:93], 7
	v_ashrrev_i32_e32 v1, 31, v0
	v_readlane_b32 s7, v236, 44
	s_movk_i32 s8, 0x2440
	v_or_b32_e32 v3, s41, v40
	v_readlane_b32 s44, v237, 25
	v_readlane_b32 s52, v237, 33
	v_readlane_b32 s53, v237, 34
	v_readlane_b32 s45, v237, 26
	v_readlane_b32 s46, v237, 27
	v_readlane_b32 s47, v237, 28
	v_readlane_b32 s48, v237, 29
	v_readlane_b32 s49, v237, 30
	v_readlane_b32 s50, v237, 31
	v_readlane_b32 s51, v237, 32
	v_readlane_b32 s54, v237, 35
	v_readlane_b32 s55, v237, 36
	v_readlane_b32 s56, v237, 37
	v_readlane_b32 s57, v237, 38
	v_readlane_b32 s58, v237, 39
	v_readlane_b32 s59, v237, 40
	v_lshl_add_u64 v[24:25], s[38:39], 0, v[0:1]
	v_mov_b64_e32 v[26:27], s[6:7]
	v_readlane_b32 s6, v236, 45
	v_readlane_b32 s7, v236, 46
	global_load_dwordx4 v[100:103], v[28:29], off
	global_load_dwordx4 v[116:119], v[32:33], off
	global_load_dwordx4 v[132:135], v[34:35], off
	global_load_dwordx4 v[148:151], v[36:37], off
	global_load_dwordx4 v[164:167], v[38:39], off
	global_load_dwordx4 v[104:107], v[28:29], off offset:64
	global_load_dwordx4 v[120:123], v[32:33], off offset:64
	global_load_dwordx4 v[136:139], v[34:35], off offset:64
	global_load_dwordx4 v[152:155], v[36:37], off offset:64
	global_load_dwordx4 v[168:171], v[38:39], off offset:64
	global_load_dwordx4 v[108:111], v[28:29], off offset:128
	global_load_dwordx4 v[124:127], v[32:33], off offset:128
	global_load_dwordx4 v[140:143], v[34:35], off offset:128
	global_load_dwordx4 v[156:159], v[36:37], off offset:128
	global_load_dwordx4 v[172:175], v[38:39], off offset:128
	global_load_dwordx4 v[112:115], v[28:29], off offset:192
	global_load_dwordx4 v[128:131], v[32:33], off offset:192
	global_load_dwordx4 v[144:147], v[34:35], off offset:192
	global_load_dwordx4 v[160:163], v[36:37], off offset:192
	global_load_dwordx4 v[176:179], v[38:39], off offset:192
	s_waitcnt vmcnt(18)
	v_mfma_f32_16x16x32_bf16 v[20:23], v[100:103], v[116:119], 0
	s_waitcnt vmcnt(17)
	v_mfma_f32_16x16x32_bf16 v[16:19], v[100:103], v[132:135], 0
	s_waitcnt vmcnt(16)
	v_mfma_f32_16x16x32_bf16 v[12:15], v[100:103], v[148:151], 0
	s_waitcnt vmcnt(15)
	v_mfma_f32_16x16x32_bf16 v[4:7], v[100:103], v[164:167], 0
	s_waitcnt vmcnt(13)
	v_mfma_f32_16x16x32_bf16 v[20:23], v[104:107], v[120:123], v[20:23]
	s_waitcnt vmcnt(12)
	v_mfma_f32_16x16x32_bf16 v[16:19], v[104:107], v[136:139], v[16:19]
	s_waitcnt vmcnt(11)
	v_mfma_f32_16x16x32_bf16 v[12:15], v[104:107], v[152:155], v[12:15]
	s_waitcnt vmcnt(10)
	v_mfma_f32_16x16x32_bf16 v[4:7], v[104:107], v[168:171], v[4:7]
	s_waitcnt vmcnt(8)
	v_mfma_f32_16x16x32_bf16 v[20:23], v[108:111], v[124:127], v[20:23]
	s_waitcnt vmcnt(7)
	v_mfma_f32_16x16x32_bf16 v[16:19], v[108:111], v[140:143], v[16:19]
	s_waitcnt vmcnt(6)
	v_mfma_f32_16x16x32_bf16 v[12:15], v[108:111], v[156:159], v[12:15]
	s_waitcnt vmcnt(5)
	v_mfma_f32_16x16x32_bf16 v[4:7], v[108:111], v[172:175], v[4:7]
	s_waitcnt vmcnt(3)
	v_mfma_f32_16x16x32_bf16 v[20:23], v[112:115], v[128:131], v[20:23]
	s_waitcnt vmcnt(2)
	v_mfma_f32_16x16x32_bf16 v[16:19], v[112:115], v[144:147], v[16:19]
	s_waitcnt vmcnt(1)
	v_mfma_f32_16x16x32_bf16 v[12:15], v[112:115], v[160:163], v[12:15]
	s_waitcnt vmcnt(0)
	v_mfma_f32_16x16x32_bf16 v[4:7], v[112:115], v[176:179], v[4:7]
	v_lshl_add_u32 v8, s40, 7, v0
	v_mad_u64_u32 v[28:29], s[40:41], v24, s8, v[26:27]
	v_mad_i32_i24 v29, v25, s8, v29
	v_lshlrev_b64 v[24:25], 11, v[24:25]
	v_lshl_add_u64 v[30:31], s[6:7], 0, v[24:25]
	v_lshlrev_b32_e32 v24, 2, v3
	v_mov_b32_e32 v25, v2
	v_lshl_add_u64 v[32:33], v[28:29], 0, v[24:25]
	global_load_dword v1, v[32:33], off
	v_mov_b32_e32 v170, 0x2440
	v_mov_b32_e32 v171, 0
	v_lshl_add_u64 v[172:173], v[32:33], 0, v[170:171]
	v_lshl_add_u64 v[174:175], v[172:173], 0, v[170:171]
	v_lshl_add_u64 v[176:177], v[174:175], 0, v[170:171]
	global_load_dword v180, v[32:33], off offset:64
	global_load_dword v181, v[32:33], off offset:128
	global_load_dword v182, v[32:33], off offset:192
	global_load_dword v183, v[172:173], off
	global_load_dword v184, v[172:173], off offset:64
	global_load_dword v185, v[172:173], off offset:128
	global_load_dword v186, v[172:173], off offset:192
	global_load_dword v187, v[174:175], off
	global_load_dword v188, v[174:175], off offset:64
	global_load_dword v189, v[174:175], off offset:128
	global_load_dword v190, v[174:175], off offset:192
	global_load_dword v191, v[176:177], off
	global_load_dword v192, v[176:177], off offset:64
	global_load_dword v193, v[176:177], off offset:128
	global_load_dword v194, v[176:177], off offset:192
	v_ashrrev_i32_e32 v9, 31, v8
	v_lshl_add_u64 v[8:9], v[8:9], 2, s[52:53]
	global_load_dwordx4 v[8:11], v[8:9], off
	s_waitcnt vmcnt(16)
	v_mul_f32_e32 v28, 0x3d372713, v1
	v_mul_f32_e32 v28, v1, v28
	v_fma_f32 v28, v1, v28, v1
	v_mul_f32_e32 v28, 0x3f4c422a, v28
	v_add_f32_e32 v28, v28, v28
	v_mul_f32_e32 v28, 0x3fb8aa3b, v28
	v_exp_f32_e32 v28, v28
	v_mul_f32_e32 v1, 0.5, v1
	s_waitcnt vmcnt(0)
	v_add_f32_e32 v20, v20, v8
	v_add_f32_e32 v28, 1.0, v28
	v_div_scale_f32 v29, s[40:41], v28, v28, 2.0
	v_rcp_f32_e32 v34, v29
	s_nop 0
	v_fma_f32 v35, -v29, v34, 1.0
	v_fmac_f32_e32 v34, v35, v34
	v_div_scale_f32 v35, vcc, 2.0, v28, 2.0
	v_mul_f32_e32 v36, v35, v34
	v_fma_f32 v37, -v29, v36, v35
	v_fmac_f32_e32 v36, v37, v34
	v_fma_f32 v29, -v29, v36, v35
	v_div_fmas_f32 v29, v29, v34, v36
	v_div_fixup_f32 v28, v29, v28, 2.0
	v_sub_f32_e32 v28, 1.0, v28
	v_add_f32_e32 v28, 1.0, v28
	v_mul_f32_e32 v1, v1, v28
	v_mul_f32_e32 v1, v20, v1
	v_bfe_u32 v20, v1, 16, 1
	v_lshlrev_b32_e32 v28, 1, v3
	v_mov_b32_e32 v29, v2
	v_add3_u32 v1, v1, v20, s27
	v_lshl_add_u64 v[30:31], v[30:31], 0, v[28:29]
	global_store_short_d16_hi v[30:31], v1, off
	v_mov_b32_e32 v1, v180
	s_nop 0
	v_mul_f32_e32 v3, 0x3d372713, v1
	v_mul_f32_e32 v3, v1, v3
	v_fma_f32 v3, v1, v3, v1
	v_mul_f32_e32 v3, 0x3f4c422a, v3
	v_add_f32_e32 v3, v3, v3
	v_mul_f32_e32 v3, 0x3fb8aa3b, v3
	v_exp_f32_e32 v3, v3
	v_mul_f32_e32 v1, 0.5, v1
	v_add_f32_e32 v3, 1.0, v3
	v_div_scale_f32 v20, s[40:41], v3, v3, 2.0
	v_rcp_f32_e32 v34, v20
	s_nop 0
	v_fma_f32 v35, -v20, v34, 1.0
	v_fmac_f32_e32 v34, v35, v34
	v_div_scale_f32 v35, vcc, 2.0, v3, 2.0
	v_mul_f32_e32 v36, v35, v34
	v_fma_f32 v37, -v20, v36, v35
	v_fmac_f32_e32 v36, v37, v34
	v_fma_f32 v20, -v20, v36, v35
	v_div_fmas_f32 v20, v20, v34, v36
	v_div_fixup_f32 v3, v20, v3, 2.0
	v_sub_f32_e32 v3, 1.0, v3
	v_add_f32_e32 v3, 1.0, v3
	v_mul_f32_e32 v1, v1, v3
	v_add_f32_e32 v3, v16, v8
	v_mul_f32_e32 v1, v3, v1
	v_bfe_u32 v3, v1, 16, 1
	v_add3_u32 v1, v1, v3, s27
	global_store_short_d16_hi v[30:31], v1, off offset:32
	v_mov_b32_e32 v1, v181
	s_nop 0
	v_mul_f32_e32 v3, 0x3d372713, v1
	v_mul_f32_e32 v3, v1, v3
	v_fma_f32 v3, v1, v3, v1
	v_mul_f32_e32 v3, 0x3f4c422a, v3
	v_add_f32_e32 v3, v3, v3
	v_mul_f32_e32 v3, 0x3fb8aa3b, v3
	v_exp_f32_e32 v3, v3
	v_mul_f32_e32 v1, 0.5, v1
	v_add_f32_e32 v3, 1.0, v3
	v_div_scale_f32 v16, s[40:41], v3, v3, 2.0
	v_rcp_f32_e32 v20, v16
	s_nop 0
	v_fma_f32 v34, -v16, v20, 1.0
	v_fmac_f32_e32 v20, v34, v20
	v_div_scale_f32 v34, vcc, 2.0, v3, 2.0
	v_mul_f32_e32 v35, v34, v20
	v_fma_f32 v36, -v16, v35, v34
	v_fmac_f32_e32 v35, v36, v20
	v_fma_f32 v16, -v16, v35, v34
	v_div_fmas_f32 v16, v16, v20, v35
	v_div_fixup_f32 v3, v16, v3, 2.0
	v_sub_f32_e32 v3, 1.0, v3
	v_add_f32_e32 v3, 1.0, v3
	v_mul_f32_e32 v1, v1, v3
	v_add_f32_e32 v3, v12, v8
	v_mul_f32_e32 v1, v3, v1
	v_bfe_u32 v3, v1, 16, 1
	v_add3_u32 v1, v1, v3, s27
	global_store_short_d16_hi v[30:31], v1, off offset:64
	v_mov_b32_e32 v1, v182
	s_nop 0
	v_mul_f32_e32 v3, 0x3d372713, v1
	v_mul_f32_e32 v3, v1, v3
	v_fma_f32 v3, v1, v3, v1
	v_mul_f32_e32 v3, 0x3f4c422a, v3
	v_add_f32_e32 v3, v3, v3
	v_mul_f32_e32 v3, 0x3fb8aa3b, v3
	v_exp_f32_e32 v3, v3
	v_mul_f32_e32 v1, 0.5, v1
	v_add_f32_e32 v3, 1.0, v3
	v_div_scale_f32 v12, s[40:41], v3, v3, 2.0
	v_rcp_f32_e32 v16, v12
	s_nop 0
	v_fma_f32 v20, -v12, v16, 1.0
	v_fmac_f32_e32 v16, v20, v16
	v_div_scale_f32 v20, vcc, 2.0, v3, 2.0
	v_mul_f32_e32 v32, v20, v16
	v_fma_f32 v33, -v12, v32, v20
	v_fmac_f32_e32 v32, v33, v16
	v_fma_f32 v12, -v12, v32, v20
	v_div_fmas_f32 v12, v12, v16, v32
	v_div_fixup_f32 v3, v12, v3, 2.0
	v_sub_f32_e32 v3, 1.0, v3
	v_add_f32_e32 v3, 1.0, v3
	v_mul_f32_e32 v1, v1, v3
	v_add_f32_e32 v3, v4, v8
	v_mul_f32_e32 v1, v3, v1
	v_bfe_u32 v3, v1, 16, 1
	v_add3_u32 v1, v1, v3, s27
	global_store_short_d16_hi v[30:31], v1, off offset:96
	v_or_b32_e32 v30, 1, v0
	v_ashrrev_i32_e32 v31, 31, v30
	v_lshl_add_u64 v[30:31], s[38:39], 0, v[30:31]
	v_mad_u64_u32 v[32:33], s[40:41], v30, s8, v[26:27]
	v_mad_i32_i24 v33, v31, s8, v33
	v_lshlrev_b64 v[30:31], 11, v[30:31]
	v_lshl_add_u64 v[34:35], s[6:7], 0, v[30:31]
	v_lshl_add_u64 v[30:31], v[32:33], 0, v[24:25]
	v_mov_b32_e32 v1, v183
	s_nop 0
	v_mul_f32_e32 v3, 0x3d372713, v1
	v_mul_f32_e32 v3, v1, v3
	v_fma_f32 v3, v1, v3, v1
	v_mul_f32_e32 v3, 0x3f4c422a, v3
	v_add_f32_e32 v3, v3, v3
	v_mul_f32_e32 v3, 0x3fb8aa3b, v3
	v_exp_f32_e32 v3, v3
	v_mul_f32_e32 v1, 0.5, v1
	v_add_f32_e32 v3, 1.0, v3
	v_div_scale_f32 v4, s[40:41], v3, v3, 2.0
	v_rcp_f32_e32 v8, v4
	s_nop 0
	v_fma_f32 v12, -v4, v8, 1.0
	v_fmac_f32_e32 v8, v12, v8
	v_div_scale_f32 v12, vcc, 2.0, v3, 2.0
	v_mul_f32_e32 v16, v12, v8
	v_fma_f32 v20, -v4, v16, v12
	v_fmac_f32_e32 v16, v20, v8
	v_fma_f32 v4, -v4, v16, v12
	v_div_fmas_f32 v4, v4, v8, v16
	v_div_fixup_f32 v3, v4, v3, 2.0
	v_sub_f32_e32 v3, 1.0, v3
	v_add_f32_e32 v3, 1.0, v3
	v_mul_f32_e32 v1, v1, v3
	v_add_f32_e32 v3, v21, v9
	v_mul_f32_e32 v1, v3, v1
	v_bfe_u32 v3, v1, 16, 1
	v_add3_u32 v1, v1, v3, s27
	v_lshl_add_u64 v[20:21], v[34:35], 0, v[28:29]
	global_store_short_d16_hi v[20:21], v1, off
	v_mov_b32_e32 v1, v184
	s_nop 0
	v_mul_f32_e32 v3, 0x3d372713, v1
	v_mul_f32_e32 v3, v1, v3
	v_fma_f32 v3, v1, v3, v1
	v_mul_f32_e32 v3, 0x3f4c422a, v3
	v_add_f32_e32 v3, v3, v3
	v_mul_f32_e32 v3, 0x3fb8aa3b, v3
	v_exp_f32_e32 v3, v3
	v_mul_f32_e32 v1, 0.5, v1
	v_add_f32_e32 v3, 1.0, v3
	v_div_scale_f32 v4, s[40:41], v3, v3, 2.0
	v_rcp_f32_e32 v8, v4
	s_nop 0
	v_fma_f32 v12, -v4, v8, 1.0
	v_fmac_f32_e32 v8, v12, v8
	v_div_scale_f32 v12, vcc, 2.0, v3, 2.0
	v_mul_f32_e32 v16, v12, v8
	v_fma_f32 v32, -v4, v16, v12
	v_fmac_f32_e32 v16, v32, v8
	v_fma_f32 v4, -v4, v16, v12
	v_div_fmas_f32 v4, v4, v8, v16
	v_div_fixup_f32 v3, v4, v3, 2.0
	v_sub_f32_e32 v3, 1.0, v3
	v_add_f32_e32 v3, 1.0, v3
	v_mul_f32_e32 v1, v1, v3
	v_add_f32_e32 v3, v17, v9
	v_mul_f32_e32 v1, v3, v1
	v_bfe_u32 v3, v1, 16, 1
	v_add3_u32 v1, v1, v3, s27
	global_store_short_d16_hi v[20:21], v1, off offset:32
	v_mov_b32_e32 v1, v185
	s_nop 0
	v_mul_f32_e32 v3, 0x3d372713, v1
	v_mul_f32_e32 v3, v1, v3
	v_fma_f32 v3, v1, v3, v1
	v_mul_f32_e32 v3, 0x3f4c422a, v3
	v_add_f32_e32 v3, v3, v3
	v_mul_f32_e32 v3, 0x3fb8aa3b, v3
	v_exp_f32_e32 v3, v3
	v_mul_f32_e32 v1, 0.5, v1
	v_add_f32_e32 v3, 1.0, v3
	v_div_scale_f32 v4, s[40:41], v3, v3, 2.0
	v_rcp_f32_e32 v8, v4
	s_nop 0
	v_fma_f32 v12, -v4, v8, 1.0
	v_fmac_f32_e32 v8, v12, v8
	v_div_scale_f32 v12, vcc, 2.0, v3, 2.0
	v_mul_f32_e32 v16, v12, v8
	v_fma_f32 v17, -v4, v16, v12
	v_fmac_f32_e32 v16, v17, v8
	v_fma_f32 v4, -v4, v16, v12
	v_div_fmas_f32 v4, v4, v8, v16
	v_div_fixup_f32 v3, v4, v3, 2.0
	v_sub_f32_e32 v3, 1.0, v3
	v_add_f32_e32 v3, 1.0, v3
	v_mul_f32_e32 v1, v1, v3
	v_add_f32_e32 v3, v13, v9
	v_mul_f32_e32 v1, v3, v1
	v_bfe_u32 v3, v1, 16, 1
	v_add3_u32 v1, v1, v3, s27
	global_store_short_d16_hi v[20:21], v1, off offset:64
	v_mov_b32_e32 v1, v186
	s_nop 0
	v_mul_f32_e32 v3, 0x3d372713, v1
	v_mul_f32_e32 v3, v1, v3
	v_fma_f32 v3, v1, v3, v1
	v_mul_f32_e32 v3, 0x3f4c422a, v3
	v_add_f32_e32 v3, v3, v3
	v_mul_f32_e32 v3, 0x3fb8aa3b, v3
	v_exp_f32_e32 v3, v3
	v_mul_f32_e32 v1, 0.5, v1
	v_add_f32_e32 v3, 1.0, v3
	v_div_scale_f32 v4, s[40:41], v3, v3, 2.0
	v_rcp_f32_e32 v8, v4
	s_nop 0
	v_fma_f32 v12, -v4, v8, 1.0
	v_fmac_f32_e32 v8, v12, v8
	v_div_scale_f32 v12, vcc, 2.0, v3, 2.0
	v_mul_f32_e32 v13, v12, v8
	v_fma_f32 v16, -v4, v13, v12
	v_fmac_f32_e32 v13, v16, v8
	v_fma_f32 v4, -v4, v13, v12
	v_div_fmas_f32 v4, v4, v8, v13
	v_div_fixup_f32 v3, v4, v3, 2.0
	v_sub_f32_e32 v3, 1.0, v3
	v_add_f32_e32 v3, 1.0, v3
	v_or_b32_e32 v4, 2, v0
	v_mul_f32_e32 v1, v1, v3
	v_add_f32_e32 v3, v5, v9
	v_ashrrev_i32_e32 v5, 31, v4
	v_lshl_add_u64 v[4:5], s[38:39], 0, v[4:5]
	v_mul_f32_e32 v1, v3, v1
	v_mad_u64_u32 v[8:9], s[40:41], v4, s8, v[26:27]
	v_bfe_u32 v3, v1, 16, 1
	v_mad_i32_i24 v9, v5, s8, v9
	v_lshlrev_b64 v[4:5], 11, v[4:5]
	v_add3_u32 v1, v1, v3, s27
	v_lshl_add_u64 v[12:13], s[6:7], 0, v[4:5]
	v_lshl_add_u64 v[4:5], v[8:9], 0, v[24:25]
	global_store_short_d16_hi v[20:21], v1, off offset:96
	v_mov_b32_e32 v1, v187
	v_or_b32_e32 v0, 3, v0
	s_nop 0
	v_mul_f32_e32 v3, 0x3d372713, v1
	v_mul_f32_e32 v3, v1, v3
	v_fma_f32 v3, v1, v3, v1
	v_mul_f32_e32 v3, 0x3f4c422a, v3
	v_add_f32_e32 v3, v3, v3
	v_mul_f32_e32 v3, 0x3fb8aa3b, v3
	v_exp_f32_e32 v3, v3
	v_mul_f32_e32 v1, 0.5, v1
	v_add_f32_e32 v3, 1.0, v3
	v_div_scale_f32 v8, s[40:41], v3, v3, 2.0
	v_rcp_f32_e32 v9, v8
	s_nop 0
	v_fma_f32 v16, -v8, v9, 1.0
	v_fmac_f32_e32 v9, v16, v9
	v_div_scale_f32 v16, vcc, 2.0, v3, 2.0
	v_mul_f32_e32 v17, v16, v9
	v_fma_f32 v20, -v8, v17, v16
	v_fmac_f32_e32 v17, v20, v9
	v_fma_f32 v8, -v8, v17, v16
	v_div_fmas_f32 v8, v8, v9, v17
	v_div_fixup_f32 v3, v8, v3, 2.0
	v_sub_f32_e32 v3, 1.0, v3
	v_add_f32_e32 v3, 1.0, v3
	v_mul_f32_e32 v1, v1, v3
	v_add_f32_e32 v3, v22, v10
	v_mul_f32_e32 v1, v3, v1
	v_bfe_u32 v3, v1, 16, 1
	v_add3_u32 v1, v1, v3, s27
	v_lshl_add_u64 v[8:9], v[12:13], 0, v[28:29]
	global_store_short_d16_hi v[8:9], v1, off
	v_mov_b32_e32 v1, v188
	s_nop 0
	v_mul_f32_e32 v3, 0x3d372713, v1
	v_mul_f32_e32 v3, v1, v3
	v_fma_f32 v3, v1, v3, v1
	v_mul_f32_e32 v3, 0x3f4c422a, v3
	v_add_f32_e32 v3, v3, v3
	v_mul_f32_e32 v3, 0x3fb8aa3b, v3
	v_exp_f32_e32 v3, v3
	v_mul_f32_e32 v1, 0.5, v1
	v_add_f32_e32 v3, 1.0, v3
	v_div_scale_f32 v12, s[40:41], v3, v3, 2.0
	v_rcp_f32_e32 v13, v12
	s_nop 0
	v_fma_f32 v16, -v12, v13, 1.0
	v_fmac_f32_e32 v13, v16, v13
	v_div_scale_f32 v16, vcc, 2.0, v3, 2.0
	v_mul_f32_e32 v17, v16, v13
	v_fma_f32 v20, -v12, v17, v16
	v_fmac_f32_e32 v17, v20, v13
	v_fma_f32 v12, -v12, v17, v16
	v_div_fmas_f32 v12, v12, v13, v17
	v_div_fixup_f32 v3, v12, v3, 2.0
	v_sub_f32_e32 v3, 1.0, v3
	v_add_f32_e32 v3, 1.0, v3
	v_mul_f32_e32 v1, v1, v3
	v_add_f32_e32 v3, v18, v10
	v_mul_f32_e32 v1, v3, v1
	v_bfe_u32 v3, v1, 16, 1
	v_add3_u32 v1, v1, v3, s27
	global_store_short_d16_hi v[8:9], v1, off offset:32
	v_mov_b32_e32 v1, v189
	s_nop 0
	v_mul_f32_e32 v3, 0x3d372713, v1
	v_mul_f32_e32 v3, v1, v3
	v_fma_f32 v3, v1, v3, v1
	v_mul_f32_e32 v3, 0x3f4c422a, v3
	v_add_f32_e32 v3, v3, v3
	v_mul_f32_e32 v3, 0x3fb8aa3b, v3
	v_exp_f32_e32 v3, v3
	v_mul_f32_e32 v1, 0.5, v1
	v_add_f32_e32 v3, 1.0, v3
	v_div_scale_f32 v12, s[40:41], v3, v3, 2.0
	v_rcp_f32_e32 v13, v12
	s_nop 0
	v_fma_f32 v16, -v12, v13, 1.0
	v_fmac_f32_e32 v13, v16, v13
	v_div_scale_f32 v16, vcc, 2.0, v3, 2.0
	v_mul_f32_e32 v17, v16, v13
	v_fma_f32 v18, -v12, v17, v16
	v_fmac_f32_e32 v17, v18, v13
	v_fma_f32 v12, -v12, v17, v16
	v_div_fmas_f32 v12, v12, v13, v17
	v_div_fixup_f32 v3, v12, v3, 2.0
	v_sub_f32_e32 v3, 1.0, v3
	v_add_f32_e32 v3, 1.0, v3
	v_mul_f32_e32 v1, v1, v3
	v_add_f32_e32 v3, v14, v10
	v_mul_f32_e32 v1, v3, v1
	v_bfe_u32 v3, v1, 16, 1
	v_add3_u32 v1, v1, v3, s27
	global_store_short_d16_hi v[8:9], v1, off offset:64
	v_mov_b32_e32 v1, v190
	s_nop 0
	v_mul_f32_e32 v3, 0x3d372713, v1
	v_mul_f32_e32 v3, v1, v3
	v_fma_f32 v3, v1, v3, v1
	v_mul_f32_e32 v3, 0x3f4c422a, v3
	v_add_f32_e32 v3, v3, v3
	v_mul_f32_e32 v3, 0x3fb8aa3b, v3
	v_exp_f32_e32 v3, v3
	v_mul_f32_e32 v1, 0.5, v1
	v_add_f32_e32 v3, 1.0, v3
	v_div_scale_f32 v4, s[40:41], v3, v3, 2.0
	v_rcp_f32_e32 v5, v4
	s_nop 0
	v_fma_f32 v12, -v4, v5, 1.0
	v_fmac_f32_e32 v5, v12, v5
	v_div_scale_f32 v12, vcc, 2.0, v3, 2.0
	v_mul_f32_e32 v13, v12, v5
	v_fma_f32 v14, -v4, v13, v12
	v_fmac_f32_e32 v13, v14, v5
	v_fma_f32 v4, -v4, v13, v12
	v_div_fmas_f32 v4, v4, v5, v13
	v_div_fixup_f32 v3, v4, v3, 2.0
	v_sub_f32_e32 v3, 1.0, v3
	v_add_f32_e32 v3, 1.0, v3
	v_mul_f32_e32 v1, v1, v3
	v_add_f32_e32 v3, v6, v10
	v_mul_f32_e32 v1, v3, v1
	v_bfe_u32 v3, v1, 16, 1
	v_add3_u32 v1, v1, v3, s27
	global_store_short_d16_hi v[8:9], v1, off offset:96
	v_ashrrev_i32_e32 v1, 31, v0
	v_lshl_add_u64 v[0:1], s[38:39], 0, v[0:1]
	v_mad_u64_u32 v[4:5], s[38:39], v0, s8, v[26:27]
	v_mad_i32_i24 v5, v1, s8, v5
	v_lshl_add_u64 v[4:5], v[4:5], 0, v[24:25]
	v_mov_b32_e32 v3, v191
	v_lshlrev_b64 v[0:1], 11, v[0:1]
	v_lshl_add_u64 v[0:1], s[6:7], 0, v[0:1]
	v_lshl_add_u64 v[0:1], v[0:1], 0, v[28:29]
	s_nop 0
	v_mul_f32_e32 v6, 0x3d372713, v3
	v_mul_f32_e32 v6, v3, v6
	v_fma_f32 v6, v3, v6, v3
	v_mul_f32_e32 v6, 0x3f4c422a, v6
	v_add_f32_e32 v6, v6, v6
	v_mul_f32_e32 v6, 0x3fb8aa3b, v6
	v_exp_f32_e32 v6, v6
	v_mul_f32_e32 v3, 0.5, v3
	v_add_f32_e32 v6, 1.0, v6
	v_div_scale_f32 v8, s[38:39], v6, v6, 2.0
	v_rcp_f32_e32 v9, v8
	s_nop 0
	v_fma_f32 v10, -v8, v9, 1.0
	v_fmac_f32_e32 v9, v10, v9
	v_div_scale_f32 v10, vcc, 2.0, v6, 2.0
	v_mul_f32_e32 v12, v10, v9
	v_fma_f32 v13, -v8, v12, v10
	v_fmac_f32_e32 v12, v13, v9
	v_fma_f32 v8, -v8, v12, v10
	v_div_fmas_f32 v8, v8, v9, v12
	v_div_fixup_f32 v6, v8, v6, 2.0
	v_sub_f32_e32 v6, 1.0, v6
	v_add_f32_e32 v6, 1.0, v6
	v_mul_f32_e32 v3, v3, v6
	v_add_f32_e32 v6, v23, v11
	v_mul_f32_e32 v3, v6, v3
	v_bfe_u32 v6, v3, 16, 1
	v_add3_u32 v3, v3, v6, s27
	global_store_short_d16_hi v[0:1], v3, off
	v_mov_b32_e32 v3, v192
	s_nop 0
	v_mul_f32_e32 v6, 0x3d372713, v3
	v_mul_f32_e32 v6, v3, v6
	v_fma_f32 v6, v3, v6, v3
	v_mul_f32_e32 v6, 0x3f4c422a, v6
	v_add_f32_e32 v6, v6, v6
	v_mul_f32_e32 v6, 0x3fb8aa3b, v6
	v_exp_f32_e32 v6, v6
	v_mul_f32_e32 v3, 0.5, v3
	v_add_f32_e32 v6, 1.0, v6
	v_div_scale_f32 v8, s[38:39], v6, v6, 2.0
	v_rcp_f32_e32 v9, v8
	s_nop 0
	v_fma_f32 v10, -v8, v9, 1.0
	v_fmac_f32_e32 v9, v10, v9
	v_div_scale_f32 v10, vcc, 2.0, v6, 2.0
	v_mul_f32_e32 v12, v10, v9
	v_fma_f32 v13, -v8, v12, v10
	v_fmac_f32_e32 v12, v13, v9
	v_fma_f32 v8, -v8, v12, v10
	v_div_fmas_f32 v8, v8, v9, v12
	v_div_fixup_f32 v6, v8, v6, 2.0
	v_sub_f32_e32 v6, 1.0, v6
	v_add_f32_e32 v6, 1.0, v6
	v_mul_f32_e32 v3, v3, v6
	v_add_f32_e32 v6, v19, v11
	v_mul_f32_e32 v3, v6, v3
	v_bfe_u32 v6, v3, 16, 1
	v_add3_u32 v3, v3, v6, s27
	global_store_short_d16_hi v[0:1], v3, off offset:32
	v_mov_b32_e32 v3, v193
	s_nop 0
	v_mul_f32_e32 v6, 0x3d372713, v3
	v_mul_f32_e32 v6, v3, v6
	v_fma_f32 v6, v3, v6, v3
	v_mul_f32_e32 v6, 0x3f4c422a, v6
	v_add_f32_e32 v6, v6, v6
	v_mul_f32_e32 v6, 0x3fb8aa3b, v6
	v_exp_f32_e32 v6, v6
	v_mul_f32_e32 v3, 0.5, v3
	v_add_f32_e32 v6, 1.0, v6
	v_div_scale_f32 v8, s[38:39], v6, v6, 2.0
	v_rcp_f32_e32 v9, v8
	s_nop 0
	v_fma_f32 v10, -v8, v9, 1.0
	v_fmac_f32_e32 v9, v10, v9
	v_div_scale_f32 v10, vcc, 2.0, v6, 2.0
	v_mul_f32_e32 v12, v10, v9
	v_fma_f32 v13, -v8, v12, v10
	v_fmac_f32_e32 v12, v13, v9
	v_fma_f32 v8, -v8, v12, v10
	v_div_fmas_f32 v8, v8, v9, v12
	v_div_fixup_f32 v6, v8, v6, 2.0
	v_sub_f32_e32 v6, 1.0, v6
	v_add_f32_e32 v6, 1.0, v6
	v_mul_f32_e32 v3, v3, v6
	v_add_f32_e32 v6, v15, v11
	v_mul_f32_e32 v3, v6, v3
	v_bfe_u32 v6, v3, 16, 1
	v_add3_u32 v3, v3, v6, s27
	global_store_short_d16_hi v[0:1], v3, off offset:64
	v_mov_b32_e32 v3, v194
	s_nop 0
	v_mul_f32_e32 v4, 0x3d372713, v3
	v_mul_f32_e32 v4, v3, v4
	v_fma_f32 v4, v3, v4, v3
	v_mul_f32_e32 v4, 0x3f4c422a, v4
	v_add_f32_e32 v4, v4, v4
	v_mul_f32_e32 v4, 0x3fb8aa3b, v4
	v_exp_f32_e32 v4, v4
	v_mul_f32_e32 v3, 0.5, v3
	v_add_f32_e32 v4, 1.0, v4
	v_div_scale_f32 v5, s[38:39], v4, v4, 2.0
	v_rcp_f32_e32 v6, v5
	s_mov_b64 s[38:39], 0
	v_fma_f32 v8, -v5, v6, 1.0
	v_fmac_f32_e32 v6, v8, v6
	v_div_scale_f32 v8, vcc, 2.0, v4, 2.0
	v_mul_f32_e32 v9, v8, v6
	v_fma_f32 v10, -v5, v9, v8
	v_fmac_f32_e32 v9, v10, v6
	v_fma_f32 v5, -v5, v9, v8
	v_div_fmas_f32 v5, v5, v6, v9
	v_div_fixup_f32 v4, v5, v4, 2.0
	v_sub_f32_e32 v4, 1.0, v4
	v_add_f32_e32 v4, 1.0, v4
	v_mul_f32_e32 v3, v3, v4
	v_add_f32_e32 v4, v7, v11
	v_mul_f32_e32 v3, v4, v3
	v_bfe_u32 v4, v3, 16, 1
	v_add3_u32 v3, v3, v4, s27
	global_store_short_d16_hi v[0:1], v3, off offset:96

.LBB0_588:
	s_or_b64 exec, exec, s[38:39]
	v_bfe_u32 v16, v0, 6, 1
	v_lshl_add_u32 v23, s42, 2, v15
	v_lshl_or_b32 v0, v15, 1, v16
	s_movk_i32 s38, 0x4200
	v_lshlrev_b32_e32 v22, 4, v16
	v_mul_lo_u32 v17, v0, s38
	v_add3_u32 v0, v23, s62, v22
	v_ashrrev_i32_e32 v1, 31, v0
	v_readlane_b32 s8, v237, 63
	v_lshlrev_b32_e32 v24, 3, v21
	v_lshlrev_b64 v[12:13], 12, v[0:1]
	v_readlane_b32 s9, v236, 0
	v_lshlrev_b32_e32 v18, 1, v3
	v_mov_b32_e32 v19, v2
	v_lshl_add_u64 v[12:13], s[8:9], 0, v[12:13]
	v_and_b32_e32 v1, 8, v24
	v_lshl_add_u64 v[12:13], v[12:13], 0, v[18:19]
	v_lshlrev_b32_e32 v18, 1, v1
	v_lshl_add_u64 v[12:13], v[12:13], 0, v[18:19]
	global_load_dwordx4 v[26:29], v[12:13], off
	global_load_dwordx4 v[34:37], v[12:13], off offset:512
	global_load_dwordx4 v[100:103], v[12:13], off offset:1024
	global_load_dwordx4 v[104:107], v[12:13], off offset:1536
	global_load_dwordx4 v[108:111], v[12:13], off offset:2048
	global_load_dwordx4 v[112:115], v[12:13], off offset:2560
	global_load_dwordx4 v[116:119], v[12:13], off offset:3072
	global_load_dwordx4 v[120:123], v[12:13], off offset:3584
	v_cmp_lt_u32_e32 vcc, 31, v14
	v_mul_u32_u24_e32 v1, 0x210, v21
	v_lshl_or_b32 v3, v20, 2, v17
	v_lshlrev_b32_e32 v1, 2, v1
	v_add_u32_e32 v18, v3, v1
	v_add_u32_e32 v19, 0x2000, v18
	v_add_u32_e32 v25, 0x2400, v18
	v_add_u32_e32 v42, 0x4000, v18
	v_add_u32_e32 v43, 0x4400, v18
	v_lshlrev_b32_e32 v3, 2, v14
	v_or_b32_e32 v44, 0xc0, v3
	v_add3_u32 v44, v17, v44, v1
	v_add_u32_e32 v45, 0x2000, v44
	v_or_b32_e32 v3, 0x1c0, v3
	v_add3_u32 v1, v17, v3, v1
	v_add_u32_e32 v3, 0x2000, v1
	v_lshl_or_b32 v0, v0, 6, v14
	v_readlane_b32 s8, v237, 61
	v_readlane_b32 s9, v237, 62
	s_cmp_lt_u32 s54, 16
	s_cselect_b64 s[40:41], -1, 0
	s_waitcnt vmcnt(7)
	v_cndmask_b32_e64 v29, v29, 0, vcc
	v_cndmask_b32_e64 v28, v28, 0, vcc
	v_cndmask_b32_e64 v27, v27, 0, vcc
	v_cndmask_b32_e64 v26, v26, 0, vcc
	s_waitcnt vmcnt(6)
	v_cndmask_b32_e64 v37, v37, 0, vcc
	v_cndmask_b32_e64 v36, v36, 0, vcc
	v_cndmask_b32_e64 v35, v35, 0, vcc
	v_cndmask_b32_e64 v34, v34, 0, vcc
	v_mfma_f32_16x16x32_bf16 v[30:33], v[8:11], v[26:29], 0
	s_nop 0
	v_mfma_f32_16x16x32_bf16 v[38:41], v[8:11], v[34:37], 0
	s_nop 7
	ds_write2_b32 v19, v30, v38 offset1:16
	ds_write2_b32 v19, v31, v39 offset0:132 offset1:148
	v_mfma_f32_16x16x32_bf16 v[26:29], v[4:7], v[26:29], 0
	ds_write2_b32 v25, v32, v40 offset0:8 offset1:24
	ds_write2_b32 v25, v33, v41 offset0:140 offset1:156
	v_mfma_f32_16x16x32_bf16 v[30:33], v[4:7], v[34:37], 0
	s_nop 7
	ds_write2_b32 v42, v26, v30 offset0:64 offset1:80
	ds_write2_b32 v42, v27, v31 offset0:196 offset1:212
	ds_write2_b32 v43, v28, v32 offset0:72 offset1:88
	ds_write2_b32 v43, v29, v33 offset0:204 offset1:220
	s_waitcnt vmcnt(5)
	v_mov_b32_e32 v26, v100
	v_mov_b32_e32 v27, v101
	v_mov_b32_e32 v28, v102
	v_mov_b32_e32 v29, v103
	s_waitcnt vmcnt(4)
	v_mov_b32_e32 v34, v104
	v_mov_b32_e32 v35, v105
	v_mov_b32_e32 v36, v106
	v_mov_b32_e32 v37, v107
	s_nop 0
	v_cndmask_b32_e64 v29, v29, 0, vcc
	s_nop 0
	v_cndmask_b32_e64 v37, v37, 0, vcc
	v_cndmask_b32_e64 v36, v36, 0, vcc
	v_cndmask_b32_e64 v35, v35, 0, vcc
	v_cndmask_b32_e64 v34, v34, 0, vcc
	v_cndmask_b32_e64 v28, v28, 0, vcc
	v_cndmask_b32_e64 v27, v27, 0, vcc
	v_mfma_f32_16x16x32_bf16 v[38:41], v[8:11], v[34:37], 0
	v_cndmask_b32_e64 v26, v26, 0, vcc
	v_mfma_f32_16x16x32_bf16 v[34:37], v[4:7], v[34:37], 0
	s_nop 0
	v_mfma_f32_16x16x32_bf16 v[30:33], v[8:11], v[26:29], 0
	s_nop 3
	ds_write2_b32 v45, v38, v39 offset1:132
	v_add_u32_e32 v38, 0x2400, v44
	ds_write2_b32 v38, v40, v41 offset0:8 offset1:140
	v_add_u32_e32 v38, 0x4000, v44
	ds_write2_b32 v38, v34, v35 offset0:64 offset1:196
	v_add_u32_e32 v34, 0x4400, v44
	ds_write2_b32 v34, v36, v37 offset0:72 offset1:204
	s_waitcnt vmcnt(3)
	v_mov_b32_e32 v34, v108
	v_mov_b32_e32 v35, v109
	v_mov_b32_e32 v36, v110
	v_mov_b32_e32 v37, v111
	v_mfma_f32_16x16x32_bf16 v[26:29], v[4:7], v[26:29], 0
	s_nop 0
	v_cndmask_b32_e64 v37, v37, 0, vcc
	v_cndmask_b32_e64 v36, v36, 0, vcc
	v_cndmask_b32_e64 v35, v35, 0, vcc
	v_cndmask_b32_e64 v34, v34, 0, vcc
	s_nop 1
	v_mfma_f32_16x16x32_bf16 v[38:41], v[8:11], v[34:37], 0
	s_nop 7
	ds_write2_b32 v19, v30, v38 offset0:32 offset1:64
	ds_write2_b32 v19, v31, v39 offset0:164 offset1:196
	ds_write2_b32 v25, v32, v40 offset0:40 offset1:72
	ds_write2_b32 v25, v33, v41 offset0:172 offset1:204
	v_mfma_f32_16x16x32_bf16 v[30:33], v[4:7], v[34:37], 0
	s_nop 7
	ds_write2_b32 v42, v26, v30 offset0:96 offset1:128
	v_add_u32_e32 v26, 0x4200, v18
	ds_write2_b32 v26, v27, v31 offset0:100 offset1:132
	ds_write2_b32 v43, v28, v32 offset0:104 offset1:136
	v_add_u32_e32 v26, 0x4600, v18
	ds_write2_b32 v26, v29, v33 offset0:108 offset1:140
	s_waitcnt vmcnt(2)
	v_mov_b32_e32 v26, v112
	v_mov_b32_e32 v27, v113
	v_mov_b32_e32 v28, v114
	v_mov_b32_e32 v29, v115
	s_waitcnt vmcnt(1)
	v_mov_b32_e32 v34, v116
	v_mov_b32_e32 v35, v117
	v_mov_b32_e32 v36, v118
	v_mov_b32_e32 v37, v119
	v_add_u32_e32 v18, 0x4800, v18
	s_nop 0
	v_cndmask_b32_e64 v29, v29, 0, vcc
	v_cndmask_b32_e64 v28, v28, 0, vcc
	v_cndmask_b32_e64 v27, v27, 0, vcc
	v_cndmask_b32_e64 v26, v26, 0, vcc
	s_nop 0
	v_cndmask_b32_e64 v37, v37, 0, vcc
	v_cndmask_b32_e64 v36, v36, 0, vcc
	v_cndmask_b32_e64 v35, v35, 0, vcc
	v_cndmask_b32_e64 v34, v34, 0, vcc
	v_mfma_f32_16x16x32_bf16 v[30:33], v[8:11], v[26:29], 0
	s_nop 0
	v_mfma_f32_16x16x32_bf16 v[38:41], v[8:11], v[34:37], 0
	s_nop 7
	ds_write2_b32 v19, v30, v38 offset0:80 offset1:96
	ds_write2_b32 v19, v31, v39 offset0:212 offset1:228
	ds_write2_b32 v25, v32, v40 offset0:88 offset1:104
	ds_write2_b32 v25, v33, v41 offset0:220 offset1:236
	v_mfma_f32_16x16x32_bf16 v[26:29], v[4:7], v[26:29], 0
	v_mfma_f32_16x16x32_bf16 v[30:33], v[4:7], v[34:37], 0
	s_nop 7
	ds_write2_b32 v42, v26, v30 offset0:144 offset1:160
	ds_write2_b32 v43, v27, v31 offset0:20 offset1:36
	ds_write2_b32 v43, v28, v32 offset0:152 offset1:168
	ds_write2_b32 v18, v29, v33 offset0:28 offset1:44
	s_waitcnt vmcnt(0)
	v_mov_b32_e32 v26, v120
	v_mov_b32_e32 v27, v121
	v_mov_b32_e32 v28, v122
	v_mov_b32_e32 v29, v123
	s_nop 0
	v_cndmask_b32_e64 v29, v29, 0, vcc
	v_cndmask_b32_e64 v28, v28, 0, vcc
	v_cndmask_b32_e64 v27, v27, 0, vcc
	v_cndmask_b32_e64 v26, v26, 0, vcc
	s_and_b64 vcc, exec, s[40:41]
	s_nop 0
	v_mfma_f32_16x16x32_bf16 v[8:11], v[8:11], v[26:29], 0
	v_mfma_f32_16x16x32_bf16 v[4:7], v[4:7], v[26:29], 0
	s_nop 6
	ds_write2_b32 v3, v8, v9 offset1:132
	v_add_u32_e32 v3, 0x2400, v1
	ds_write2_b32 v3, v10, v11 offset0:8 offset1:140
	v_add_u32_e32 v3, 0x4000, v1
	v_add_u32_e32 v1, 0x4400, v1
	ds_write2_b32 v1, v6, v7 offset0:72 offset1:204
	v_ashrrev_i32_e32 v1, 31, v0
	v_lshlrev_b64 v[0:1], 5, v[0:1]
	ds_write2_b32 v3, v4, v5 offset0:64 offset1:196
	v_lshl_add_u64 v[4:5], s[8:9], 0, v[0:1]
	s_waitcnt lgkmcnt(0)
	s_barrier
	global_load_dwordx2 v[0:1], v[4:5], off
	global_load_dwordx2 v[6:7], v[4:5], off offset:16
	s_cbranch_vccnz .LBB0_590
	s_lshl_b32 s38, s54, 6
	s_add_i32 s38, s19, s38
	v_add3_u32 v3, s38, v23, v22
	v_lshl_or_b32 v4, v3, 6, v14
	v_ashrrev_i32_e32 v5, 31, v4
	v_lshlrev_b64 v[8:9], 2, v[4:5]
	v_lshl_add_u64 v[4:5], s[74:75], 0, v[8:9]
	v_lshl_add_u64 v[8:9], s[76:77], 0, v[8:9]
	global_load_dword v4, v[4:5], off
	s_nop 0
	global_load_dword v5, v[8:9], off
	s_branch .LBB0_591

.LBB0_668:
	s_and_b64 vcc, exec, s[38:39]
	s_cbranch_vccz .LBB0_674
	s_add_i32 s38, s60, 0xfffffcd0
	s_lshr_b32 s54, s38, 4
	s_and_b32 s47, s60, 15
	v_mov_b32_e32 v3, v206
	s_movk_i32 s39, 0x840
	s_lshl_b32 s35, s54, 7
	s_lshl_b32 s37, s47, 6
	v_cmp_gt_i32_e32 vcc, s39, v3
	s_and_saveexec_b64 s[48:49], vcc
	s_cbranch_execz .LBB0_695
	s_and_b32 s39, s35, 0xf00
	s_and_b32 s51, s35, 0x1c00
	s_add_i32 s50, s39, 0x100
	s_add_i32 s55, s51, 0x400
	s_cmpk_lt_u32 s38, 0x200
	s_cselect_b32 s55, s50, s55
	s_cselect_b32 s56, s39, s51
	s_add_i32 s57, s35, -2
	s_lshl_b32 s92, s37, 2
	v_and_b32_e32 v120, 15, v206
	v_lshlrev_b32_e32 v121, 4, v120
	v_ashrrev_i32_e32 v122, 4, v206
	v_add_u32_e32 v123, s57, v122
	s_add_u32 s4, s92, 0x3a24800
	v_add_u32_e32 v124, s4, v121
	s_movk_i32 s5, 0x2440
	v_mul_u32_u24_e32 v125, 0x104, v122
	v_add_u32_e32 v125, v125, v121
	s_mov_b64 s[58:59], exec
	v_mov_b32_e32 v126, v123
	v_cmp_le_i32_e32 vcc, s56, v126
	v_cmp_gt_i32_e64 s[38:39], s55, v126
	v_mov_b32_e32 v100, 0
	v_mov_b32_e32 v101, 0
	v_mov_b32_e32 v102, 0
	v_mov_b32_e32 v103, 0
	s_and_b64 s[38:39], vcc, s[38:39]
	v_mul_lo_u32 v127, v126, s5
	v_add_u32_e32 v127, v127, v124
	s_and_b64 exec, s[58:59], s[38:39]
	global_load_dwordx4 v[100:103], v127, s[96:97]
	s_mov_b64 exec, s[58:59]
	v_add_u32_e32 v126, 32, v123
	v_cmp_le_i32_e32 vcc, s56, v126
	v_cmp_gt_i32_e64 s[38:39], s55, v126
	v_mov_b32_e32 v104, 0
	v_mov_b32_e32 v105, 0
	v_mov_b32_e32 v106, 0
	v_mov_b32_e32 v107, 0
	s_and_b64 s[38:39], vcc, s[38:39]
	v_mul_lo_u32 v127, v126, s5
	v_add_u32_e32 v127, v127, v124
	s_and_b64 exec, s[58:59], s[38:39]
	global_load_dwordx4 v[104:107], v127, s[96:97]
	s_mov_b64 exec, s[58:59]
	v_add_u32_e32 v126, 64, v123
	v_cmp_le_i32_e32 vcc, s56, v126
	v_cmp_gt_i32_e64 s[38:39], s55, v126
	v_mov_b32_e32 v108, 0
	v_mov_b32_e32 v109, 0
	v_mov_b32_e32 v110, 0
	v_mov_b32_e32 v111, 0
	s_and_b64 s[38:39], vcc, s[38:39]
	v_mul_lo_u32 v127, v126, s5
	v_add_u32_e32 v127, v127, v124
	s_and_b64 exec, s[58:59], s[38:39]
	global_load_dwordx4 v[108:111], v127, s[96:97]
	s_mov_b64 exec, s[58:59]
	v_add_u32_e32 v126, 96, v123
	v_cmp_le_i32_e32 vcc, s56, v126
	v_cmp_gt_i32_e64 s[38:39], s55, v126
	v_mov_b32_e32 v112, 0
	v_mov_b32_e32 v113, 0
	v_mov_b32_e32 v114, 0
	v_mov_b32_e32 v115, 0
	s_and_b64 s[38:39], vcc, s[38:39]
	v_mul_lo_u32 v127, v126, s5
	v_add_u32_e32 v127, v127, v124
	s_and_b64 exec, s[58:59], s[38:39]
	global_load_dwordx4 v[112:115], v127, s[96:97]
	s_mov_b64 exec, s[58:59]
	v_add_u32_e32 v126, 128, v123
	v_cmp_le_i32_e32 vcc, s56, v126
	v_cmp_gt_i32_e64 s[38:39], s55, v126
	v_mov_b32_e32 v116, 0
	v_mov_b32_e32 v117, 0
	v_mov_b32_e32 v118, 0
	v_mov_b32_e32 v119, 0
	s_and_b64 s[38:39], vcc, s[38:39]
	v_cmp_gt_u32_e64 s[50:51], 64, v206
	v_mul_lo_u32 v127, v126, s5
	s_and_b64 s[38:39], s[38:39], s[50:51]
	v_add_u32_e32 v127, v127, v124
	s_and_b64 exec, s[58:59], s[38:39]
	global_load_dwordx4 v[116:119], v127, s[96:97]
	s_mov_b64 exec, s[58:59]
	s_waitcnt vmcnt(0)
	ds_write2_b32 v125, v100, v101 offset1:1
	ds_write2_b32 v125, v102, v103 offset0:2 offset1:3
	v_add_u32_e32 v126, 0x2080, v125
	ds_write2_b32 v126, v104, v105 offset1:1
	ds_write2_b32 v126, v106, v107 offset0:2 offset1:3
	v_add_u32_e32 v126, 0x4100, v125
	ds_write2_b32 v126, v108, v109 offset1:1
	ds_write2_b32 v126, v110, v111 offset0:2 offset1:3
	v_add_u32_e32 v126, 0x6180, v125
	ds_write2_b32 v126, v112, v113 offset1:1
	ds_write2_b32 v126, v114, v115 offset0:2 offset1:3
	s_and_b64 exec, s[58:59], s[50:51]
	v_add_u32_e32 v126, 0x8200, v125
	ds_write2_b32 v126, v116, v117 offset1:1
	ds_write2_b32 v126, v118, v119 offset0:2 offset1:3
	s_mov_b64 exec, s[58:59]
	s_branch .LBB0_695

.LBB0_684:
	s_or_b64 exec, exec, s[38:39]
	v_bfe_u32 v14, v0, 6, 1
	v_lshlrev_b32_e32 v0, 6, v1
	v_lshl_or_b32 v0, v14, 5, v0
	v_lshl_add_u32 v15, s47, 2, v1
	v_mul_lo_u32 v16, v0, s86
	v_lshlrev_b32_e32 v0, 4, v14
	v_add3_u32 v0, v15, s62, v0
	v_ashrrev_i32_e32 v1, 31, v0
	v_readlane_b32 s4, v237, 63
	v_lshlrev_b32_e32 v19, 3, v17
	v_lshlrev_b64 v[20:21], 12, v[0:1]
	v_readlane_b32 s5, v236, 0
	v_lshlrev_b32_e32 v12, 1, v12
	v_mov_b32_e32 v13, v2
	v_lshl_add_u64 v[20:21], s[4:5], 0, v[20:21]
	v_and_b32_e32 v1, 8, v19
	v_lshl_add_u64 v[12:13], v[20:21], 0, v[12:13]
	v_lshlrev_b32_e32 v20, 1, v1
	v_mov_b32_e32 v21, v2
	v_lshl_add_u64 v[12:13], v[12:13], 0, v[20:21]
	global_load_dwordx4 v[20:23], v[12:13], off
	global_load_dwordx4 v[28:31], v[12:13], off offset:512
	global_load_dwordx4 v[100:103], v[12:13], off offset:1024
	global_load_dwordx4 v[104:107], v[12:13], off offset:1536
	global_load_dwordx4 v[108:111], v[12:13], off offset:2048
	global_load_dwordx4 v[112:115], v[12:13], off offset:2560
	global_load_dwordx4 v[116:119], v[12:13], off offset:3072
	global_load_dwordx4 v[120:123], v[12:13], off offset:3584
	v_cmp_lt_u32_e32 vcc, 31, v3
	v_mul_u32_u24_e32 v1, 0x210, v17
	v_lshl_or_b32 v17, v18, 2, v16
	v_lshlrev_b32_e32 v1, 2, v1
	v_add_u32_e32 v36, v17, v1
	v_add_u32_e32 v37, 0x2000, v36
	v_add_u32_e32 v38, 0x2400, v36
	v_lshlrev_b32_e32 v17, 2, v3
	v_or_b32_e32 v39, 0xc0, v17
	v_add3_u32 v39, v16, v39, v1
	v_add_u32_e32 v40, 0x2000, v39
	v_lshl_or_b32 v0, v0, 6, v3
	v_readlane_b32 s4, v237, 61
	v_readlane_b32 s5, v237, 62
	s_mov_b32 s38, 24
	s_waitcnt vmcnt(7)
	v_cndmask_b32_e64 v23, v23, 0, vcc
	v_cndmask_b32_e64 v22, v22, 0, vcc
	v_cndmask_b32_e64 v21, v21, 0, vcc
	v_cndmask_b32_e64 v20, v20, 0, vcc
	s_waitcnt vmcnt(6)
	v_cndmask_b32_e64 v31, v31, 0, vcc
	v_cndmask_b32_e64 v30, v30, 0, vcc
	v_cndmask_b32_e64 v29, v29, 0, vcc
	v_cndmask_b32_e64 v28, v28, 0, vcc
	v_mfma_f32_16x16x32_bf16 v[24:27], v[8:11], v[20:23], 0
	s_nop 0
	v_mfma_f32_16x16x32_bf16 v[32:35], v[8:11], v[28:31], 0
	s_nop 7
	ds_write2_b32 v37, v24, v32 offset1:16
	ds_write2_b32 v37, v25, v33 offset0:132 offset1:148
	v_mfma_f32_16x16x32_bf16 v[18:21], v[4:7], v[20:23], 0
	ds_write2_b32 v38, v26, v34 offset0:8 offset1:24
	ds_write2_b32 v38, v27, v35 offset0:140 offset1:156
	v_add_u32_e32 v34, 0x4000, v36
	v_add_u32_e32 v35, 0x4400, v36
	v_mfma_f32_16x16x32_bf16 v[22:25], v[4:7], v[28:31], 0
	s_nop 7
	ds_write2_b32 v34, v18, v22 offset0:64 offset1:80
	ds_write2_b32 v34, v19, v23 offset0:196 offset1:212
	ds_write2_b32 v35, v20, v24 offset0:72 offset1:88
	ds_write2_b32 v35, v21, v25 offset0:204 offset1:220
	s_waitcnt vmcnt(5)
	v_mov_b32_e32 v18, v100
	v_mov_b32_e32 v19, v101
	v_mov_b32_e32 v20, v102
	v_mov_b32_e32 v21, v103
	s_waitcnt vmcnt(4)
	v_mov_b32_e32 v26, v104
	v_mov_b32_e32 v27, v105
	v_mov_b32_e32 v28, v106
	v_mov_b32_e32 v29, v107
	s_nop 0
	v_cndmask_b32_e64 v21, v21, 0, vcc
	s_nop 0
	v_cndmask_b32_e64 v29, v29, 0, vcc
	v_cndmask_b32_e64 v28, v28, 0, vcc
	v_cndmask_b32_e64 v27, v27, 0, vcc
	v_cndmask_b32_e64 v26, v26, 0, vcc
	v_cndmask_b32_e64 v20, v20, 0, vcc
	v_cndmask_b32_e64 v19, v19, 0, vcc
	v_mfma_f32_16x16x32_bf16 v[30:33], v[8:11], v[26:29], 0
	v_cndmask_b32_e64 v18, v18, 0, vcc
	v_mfma_f32_16x16x32_bf16 v[26:29], v[4:7], v[26:29], 0
	s_nop 0
	v_mfma_f32_16x16x32_bf16 v[22:25], v[8:11], v[18:21], 0
	s_nop 3
	ds_write2_b32 v40, v30, v31 offset1:132
	v_add_u32_e32 v30, 0x2400, v39
	ds_write2_b32 v30, v32, v33 offset0:8 offset1:140
	v_add_u32_e32 v30, 0x4000, v39
	ds_write2_b32 v30, v26, v27 offset0:64 offset1:196
	v_add_u32_e32 v26, 0x4400, v39
	ds_write2_b32 v26, v28, v29 offset0:72 offset1:204
	s_waitcnt vmcnt(3)
	v_mov_b32_e32 v26, v108
	v_mov_b32_e32 v27, v109
	v_mov_b32_e32 v28, v110
	v_mov_b32_e32 v29, v111
	v_mfma_f32_16x16x32_bf16 v[18:21], v[4:7], v[18:21], 0
	s_nop 0
	v_cndmask_b32_e64 v29, v29, 0, vcc
	v_cndmask_b32_e64 v28, v28, 0, vcc
	v_cndmask_b32_e64 v27, v27, 0, vcc
	v_cndmask_b32_e64 v26, v26, 0, vcc
	s_nop 1
	v_mfma_f32_16x16x32_bf16 v[30:33], v[8:11], v[26:29], 0
	s_nop 7
	ds_write2_b32 v37, v22, v30 offset0:32 offset1:64
	ds_write2_b32 v37, v23, v31 offset0:164 offset1:196
	ds_write2_b32 v38, v24, v32 offset0:40 offset1:72
	ds_write2_b32 v38, v25, v33 offset0:172 offset1:204
	v_mfma_f32_16x16x32_bf16 v[22:25], v[4:7], v[26:29], 0
	s_nop 7
	ds_write2_b32 v34, v18, v22 offset0:96 offset1:128
	v_add_u32_e32 v18, 0x4200, v36
	ds_write2_b32 v18, v19, v23 offset0:100 offset1:132
	ds_write2_b32 v35, v20, v24 offset0:104 offset1:136
	v_add_u32_e32 v18, 0x4600, v36
	ds_write2_b32 v18, v21, v25 offset0:108 offset1:140
	s_waitcnt vmcnt(2)
	v_mov_b32_e32 v18, v112
	v_mov_b32_e32 v19, v113
	v_mov_b32_e32 v20, v114
	v_mov_b32_e32 v21, v115
	s_waitcnt vmcnt(1)
	v_mov_b32_e32 v26, v116
	v_mov_b32_e32 v27, v117
	v_mov_b32_e32 v28, v118
	v_mov_b32_e32 v29, v119
	s_nop 0
	v_cndmask_b32_e64 v21, v21, 0, vcc
	v_cndmask_b32_e64 v20, v20, 0, vcc
	v_cndmask_b32_e64 v19, v19, 0, vcc
	v_cndmask_b32_e64 v18, v18, 0, vcc
	s_nop 0
	v_cndmask_b32_e64 v29, v29, 0, vcc
	v_cndmask_b32_e64 v28, v28, 0, vcc
	v_cndmask_b32_e64 v27, v27, 0, vcc
	v_cndmask_b32_e64 v26, v26, 0, vcc
	v_mfma_f32_16x16x32_bf16 v[22:25], v[8:11], v[18:21], 0
	s_nop 0
	v_mfma_f32_16x16x32_bf16 v[30:33], v[8:11], v[26:29], 0
	s_nop 7
	ds_write2_b32 v37, v22, v30 offset0:80 offset1:96
	ds_write2_b32 v37, v23, v31 offset0:212 offset1:228
	ds_write2_b32 v38, v24, v32 offset0:88 offset1:104
	ds_write2_b32 v38, v25, v33 offset0:220 offset1:236
	v_mfma_f32_16x16x32_bf16 v[18:21], v[4:7], v[18:21], 0
	v_mfma_f32_16x16x32_bf16 v[22:25], v[4:7], v[26:29], 0
	s_nop 7
	ds_write2_b32 v34, v18, v22 offset0:144 offset1:160
	ds_write2_b32 v35, v19, v23 offset0:20 offset1:36
	ds_write2_b32 v35, v20, v24 offset0:152 offset1:168
	v_add_u32_e32 v18, 0x4800, v36
	ds_write2_b32 v18, v21, v25 offset0:28 offset1:44
	s_waitcnt vmcnt(0)
	v_mov_b32_e32 v18, v120
	v_mov_b32_e32 v19, v121
	v_mov_b32_e32 v20, v122
	v_mov_b32_e32 v21, v123
	v_or_b32_e32 v12, 0x1c0, v17
	v_add3_u32 v1, v16, v12, v1
	v_add_u32_e32 v12, 0x2000, v1
	s_nop 0
	v_cndmask_b32_e64 v21, v21, 0, vcc
	v_cndmask_b32_e64 v20, v20, 0, vcc
	v_cndmask_b32_e64 v19, v19, 0, vcc
	v_cndmask_b32_e64 v18, v18, 0, vcc
	v_cmp_eq_u32_e32 vcc, 0, v14
	s_nop 0
	v_mfma_f32_16x16x32_bf16 v[8:11], v[8:11], v[18:21], 0
	v_mfma_f32_16x16x32_bf16 v[4:7], v[4:7], v[18:21], 0
	s_nop 6
	ds_write2_b32 v12, v8, v9 offset1:132
	v_add_u32_e32 v8, 0x2400, v1
	ds_write2_b32 v8, v10, v11 offset0:8 offset1:140
	v_add_u32_e32 v8, 0x4000, v1
	v_add_u32_e32 v1, 0x4400, v1
	ds_write2_b32 v1, v6, v7 offset0:72 offset1:204
	v_ashrrev_i32_e32 v1, 31, v0
	v_lshlrev_b64 v[0:1], 5, v[0:1]
	v_lshl_add_u64 v[0:1], s[4:5], 0, v[0:1]
	ds_write2_b32 v8, v4, v5 offset0:64 offset1:196
	s_waitcnt lgkmcnt(0)
	s_barrier
	global_load_dwordx2 v[0:1], v[0:1], off
	v_lshl_add_u32 v4, v3, 3, v16
	v_mov_b32_e32 v8, 0
	v_mov_b32_e32 v10, 0
	s_waitcnt vmcnt(0)
	v_pk_mov_b32 v[6:7], v[0:1], v[0:1] op_sel:[1,0]
